# v27 + GLA items (gla1, gla3): b_alpha loaded first, one counted vmcnt after the barrier covers the q/k/gate rows so the cumulative-decay math overlaps the remaining v/state/r loads; full wait kept bef
# speedup vs baseline: 1.0133x; 1.0082x over previous
; #define LAS __attribute__((address_space(3)))
; __device__ __forceinline__ int otid() { int t = threadIdx.x; asm volatile("" : "+v"(t)); return t; }
; __device__ __forceinline__ void gla_issue_loads(GlaLoads& L, const bf16_t* proj, int b, int h, int n, int dk, int seg, int t4, bool want_q) {
; #pragma unroll
;     for (int i = 0; i < 16; ++i) { const int rb = n * 64 + seg * 16 + i, rc = rb < TB ? rb : TB - 1; const bf16_t* rp = proj + (size_t)(b * TB + rc) * NPROJ + h * 64 + dk;
;         L.xl[i] = rp[C_GL]; L.xk[i] = rp[C_K]; if (want_q) L.xq[i] = rp[C_Q]; }
; __device__ void gla3_item(const Params& p, int l, int item, LAS unsigned char* lds) {
;     const int t = otid(), half = t >> 8, t4 = t & 255, wv = (t >> 6) & 3, lane = t & 63, fr = lane & 15, fq = lane >> 4;
;     const int pair = item % (GCH / 2), bh = item / (GCH / 2), b = bh >> 2, h = bh & 3, n = pair * 2 + half;
;     bf16_t* proj = (bf16_t*)(p.ws + WS_PROJ);
;     LAS unsigned char* hl = lds + half * GL_HALF;
;     const int dk = t4 & 63, seg = t4 >> 6;
;     GlaLoads L; gla_issue_loads(L, proj, b, h, n, dk, seg, t4, true);
.LBB0_449:
	s_cmpk_gt_i32 s29, 0x1ff
	s_mov_b64 s[10:11], -1
	s_cbranch_scc0 .LBB0_523
	s_add_i32 s10, s29, 0xfe00
	s_and_b32 s11, s10, 0xffff
	s_mul_i32 s14, s11, 0xf83f
	s_lshr_b32 s11, s14, 21
	s_mul_i32 s15, s11, 33
	s_sub_i32 s10, s10, s15
	v_mov_b32_e32 v71, v228
	s_lshl_b32 s10, s10, 1
	s_bfe_u32 s15, s14, 0x20015
	v_ashrrev_i32_e32 v160, 8, v71
	s_and_b32 s10, s10, 0xfffe
	s_lshr_b32 s22, s14, 23
	s_waitcnt vmcnt(0)
	v_add_u32_e32 v2, s10, v160
	s_lshl_b32 s14, s15, 7
	v_and_b32_e32 v149, 63, v71
	s_lshl_b32 s100, s15, 8
	s_add_u32 s100, s3, s100
	s_addc_u32 s101, s18, 0
	v_lshlrev_b32_e32 v250, 2, v149
	global_load_dword v251, v250, s[100:101]
	v_bfe_u32 v74, v71, 6, 2
	v_lshlrev_b32_e32 v70, 6, v2
	s_add_u32 s40, s20, s14
	v_lshl_or_b32 v192, v74, 4, v70
	s_addc_u32 s41, s21, 0
	v_lshlrev_b32_e32 v0, 1, v149
	s_mul_i32 s10, s22, 0x1020
	v_lshl_add_u64 v[4:5], s[40:41], 0, v[0:1]
	v_min_i32_e32 v0, 0x101f, v192
	v_add_u32_e32 v0, s10, v0
	v_or_b32_e32 v189, 1, v192
	s_waitcnt lgkmcnt(0)
	v_mad_i64_i32 v[6:7], s[40:41], v0, s96, v[4:5]
	s_movk_i32 s22, 0x1000
	v_min_i32_e32 v0, 0x101f, v189
	v_add_co_u32_e32 v8, vcc, s22, v6
	v_add_u32_e32 v0, s10, v0
	v_or_b32_e32 v188, 2, v192
	v_addc_co_u32_e32 v9, vcc, 0, v7, vcc
	v_mad_i64_i32 v[10:11], s[40:41], v0, s96, v[4:5]
	v_min_i32_e32 v0, 0x101f, v188
	v_add_co_u32_e32 v12, vcc, s22, v10
	v_add_u32_e32 v0, s10, v0
	v_or_b32_e32 v186, 3, v192
	v_addc_co_u32_e32 v13, vcc, 0, v11, vcc
	v_mad_i64_i32 v[14:15], s[40:41], v0, s96, v[4:5]
	v_min_i32_e32 v0, 0x101f, v186
	global_load_ushort v193, v[8:9], off
	global_load_ushort v191, v[12:13], off
	global_load_ushort v148, v[14:15], off offset:1536
	global_load_ushort v150, v[14:15], off offset:1024
	global_load_ushort v157, v[10:11], off offset:1536
	global_load_ushort v158, v[10:11], off offset:1024
	global_load_ushort v159, v[6:7], off offset:1536
	global_load_ushort v161, v[6:7], off offset:1024
	v_add_co_u32_e32 v6, vcc, s22, v14
	v_add_u32_e32 v0, s10, v0
	v_or_b32_e32 v184, 4, v192
	v_addc_co_u32_e32 v7, vcc, 0, v15, vcc
	v_mad_i64_i32 v[8:9], s[40:41], v0, s96, v[4:5]
	v_min_i32_e32 v0, 0x101f, v184
	v_add_co_u32_e32 v10, vcc, s22, v8
	v_add_u32_e32 v0, s10, v0
	v_or_b32_e32 v182, 5, v192
	v_addc_co_u32_e32 v11, vcc, 0, v9, vcc
	v_mad_i64_i32 v[12:13], s[40:41], v0, s96, v[4:5]
	v_min_i32_e32 v0, 0x101f, v182
	v_add_co_u32_e32 v14, vcc, s22, v12
	v_add_u32_e32 v0, s10, v0
	v_or_b32_e32 v180, 6, v192
	v_addc_co_u32_e32 v15, vcc, 0, v13, vcc
	v_mad_i64_i32 v[16:17], s[40:41], v0, s96, v[4:5]
	v_min_i32_e32 v0, 0x101f, v180
	global_load_ushort v190, v[6:7], off
	global_load_ushort v187, v[10:11], off
	global_load_ushort v185, v[14:15], off
	global_load_ushort v143, v[16:17], off offset:1024
	global_load_ushort v145, v[12:13], off offset:1536
	global_load_ushort v147, v[12:13], off offset:1024
	global_load_ushort v152, v[8:9], off offset:1536
	global_load_ushort v156, v[8:9], off offset:1024
	v_add_co_u32_e32 v6, vcc, s22, v16
	v_add_u32_e32 v0, s10, v0
	v_or_b32_e32 v178, 7, v192
	v_addc_co_u32_e32 v7, vcc, 0, v17, vcc
	v_mad_i64_i32 v[8:9], s[40:41], v0, s96, v[4:5]
	v_min_i32_e32 v0, 0x101f, v178
	v_add_co_u32_e32 v10, vcc, s22, v8
	v_add_u32_e32 v0, s10, v0
	v_or_b32_e32 v176, 8, v192
	v_addc_co_u32_e32 v11, vcc, 0, v9, vcc
	v_mad_i64_i32 v[12:13], s[40:41], v0, s96, v[4:5]
	v_min_i32_e32 v0, 0x101f, v176
	v_add_co_u32_e32 v14, vcc, s22, v12
	v_add_u32_e32 v0, s10, v0
	v_or_b32_e32 v173, 9, v192
	v_addc_co_u32_e32 v15, vcc, 0, v13, vcc
	global_load_ushort v183, v[6:7], off
	global_load_ushort v181, v[10:11], off
	global_load_ushort v179, v[14:15], off
	global_load_ushort v134, v[12:13], off offset:1536
	global_load_ushort v136, v[12:13], off offset:1024
	global_load_ushort v138, v[8:9], off offset:1536
	global_load_ushort v140, v[8:9], off offset:1024
	global_load_ushort v146, v[16:17], off offset:1536
	v_mad_i64_i32 v[6:7], s[40:41], v0, s96, v[4:5]
	v_min_i32_e32 v0, 0x101f, v173
	v_add_co_u32_e32 v8, vcc, s22, v6
	v_add_u32_e32 v0, s10, v0
	v_or_b32_e32 v172, 10, v192
	v_addc_co_u32_e32 v9, vcc, 0, v7, vcc
	v_mad_i64_i32 v[10:11], s[40:41], v0, s96, v[4:5]
	v_min_i32_e32 v0, 0x101f, v172
	v_add_co_u32_e32 v12, vcc, s22, v10
	v_add_u32_e32 v0, s10, v0
	v_or_b32_e32 v170, 11, v192
	v_addc_co_u32_e32 v13, vcc, 0, v11, vcc
	v_mad_i64_i32 v[14:15], s[40:41], v0, s96, v[4:5]
	v_min_i32_e32 v0, 0x101f, v170
	global_load_ushort v177, v[8:9], off
	global_load_ushort v175, v[12:13], off
	global_load_ushort v121, v[14:15], off offset:1536
	global_load_ushort v125, v[14:15], off offset:1024
	global_load_ushort v128, v[10:11], off offset:1536
	global_load_ushort v133, v[10:11], off offset:1024
	global_load_ushort v135, v[6:7], off offset:1536
	global_load_ushort v137, v[6:7], off offset:1024
	v_add_co_u32_e32 v6, vcc, s22, v14
	v_add_u32_e32 v0, s10, v0
	v_or_b32_e32 v168, 12, v192
	v_addc_co_u32_e32 v7, vcc, 0, v15, vcc
	v_mad_i64_i32 v[8:9], s[40:41], v0, s96, v[4:5]
	v_min_i32_e32 v0, 0x101f, v168
	v_add_co_u32_e32 v10, vcc, s22, v8
	v_add_u32_e32 v0, s10, v0
	v_or_b32_e32 v166, 13, v192
	v_addc_co_u32_e32 v11, vcc, 0, v9, vcc
	v_mad_i64_i32 v[12:13], s[40:41], v0, s96, v[4:5]
	v_min_i32_e32 v0, 0x101f, v166
	v_add_co_u32_e32 v14, vcc, s22, v12
	v_add_u32_e32 v0, s10, v0
	v_or_b32_e32 v164, 14, v192
	v_addc_co_u32_e32 v15, vcc, 0, v13, vcc
	v_mad_i64_i32 v[16:17], s[40:41], v0, s96, v[4:5]
	v_min_i32_e32 v0, 0x101f, v164
	global_load_ushort v174, v[6:7], off
	global_load_ushort v171, v[10:11], off
	global_load_ushort v169, v[14:15], off
	global_load_ushort v106, v[16:17], off offset:1024
	global_load_ushort v110, v[12:13], off offset:1536
; __device__ __forceinline__ void gla_issue_loads(GlaLoads& L, const bf16_t* proj, int b, int h, int n, int dk, int seg, int t4, bool want_q) {
; #pragma unroll
;     for (int i = 0; i < 16; ++i) { const int rb = n * 64 + seg * 16 + i, rc = rb < TB ? rb : TB - 1; const bf16_t* rp = proj + (size_t)(b * TB + rc) * NPROJ + h * 64 + dk;
;         L.xl[i] = rp[C_GL]; L.xk[i] = rp[C_K]; if (want_q) L.xq[i] = rp[C_Q]; }
; #pragma unroll
;     for (int q = 0; q < 4; ++q) { const int task = t4 + 256 * q, dv = task & 127, rg = task >> 7;
; #pragma unroll
;         for (int j = 0; j < 8; ++j) { const int rb = n * 64 + rg * 8 + j, rc = rb < TB ? rb : TB - 1; L.vv[q][j] = proj[(size_t)(b * TB + rc) * NPROJ + C_V + h * 128 + dv]; } }
	global_load_ushort v119, v[12:13], off offset:1024
	global_load_ushort v126, v[8:9], off offset:1536
	global_load_ushort v127, v[8:9], off offset:1024
	v_add_co_u32_e32 v6, vcc, s22, v16
	v_add_u32_e32 v0, s10, v0
	v_or_b32_e32 v162, 15, v192
	v_addc_co_u32_e32 v7, vcc, 0, v17, vcc
	v_mad_i64_i32 v[8:9], s[40:41], v0, s96, v[4:5]
	v_min_i32_e32 v0, 0x101f, v162
	v_add_co_u32_e32 v10, vcc, s22, v8
	v_add_u32_e32 v0, s10, v0
	s_nop 0
	v_addc_co_u32_e32 v11, vcc, 0, v9, vcc
	v_mad_i64_i32 v[4:5], s[40:41], v0, s96, v[4:5]
	v_lshrrev_b32_e32 v0, 4, v71
	v_add_co_u32_e32 v12, vcc, s22, v4
	v_and_or_b32 v3, v0, 8, v70
	s_nop 0
	v_addc_co_u32_e32 v13, vcc, 0, v5, vcc
	global_load_ushort v167, v[6:7], off
	global_load_ushort v165, v[10:11], off
	global_load_ushort v163, v[12:13], off
	global_load_ushort v73, v[4:5], off offset:1536
	global_load_ushort v78, v[4:5], off offset:1024
	global_load_ushort v81, v[8:9], off offset:1536
	global_load_ushort v104, v[8:9], off offset:1024
	global_load_ushort v112, v[16:17], off offset:1536
	v_or_b32_e32 v6, 1, v3
	v_or_b32_e32 v8, 2, v3
	v_or_b32_e32 v10, 3, v3
	v_or_b32_e32 v12, 4, v3
	v_or_b32_e32 v14, 5, v3
	v_or_b32_e32 v16, 6, v3
	v_min_i32_e32 v0, 0x101f, v3
	v_min_i32_e32 v6, 0x101f, v6
	v_min_i32_e32 v8, 0x101f, v8
	v_min_i32_e32 v10, 0x101f, v10
	v_min_i32_e32 v12, 0x101f, v12
	v_min_i32_e32 v14, 0x101f, v14
	v_min_i32_e32 v16, 0x101f, v16
	v_or_b32_e32 v18, 7, v3
	v_add_u32_e32 v0, s10, v0
	v_mov_b64_e32 v[68:69], s[20:21]
	v_add_u32_e32 v6, s10, v6
	v_add_u32_e32 v8, s10, v8
	v_add_u32_e32 v10, s10, v10
	v_add_u32_e32 v12, s10, v12
	v_add_u32_e32 v14, s10, v14
	v_add_u32_e32 v16, s10, v16
	v_min_i32_e32 v18, 0x101f, v18
	v_and_b32_e32 v72, 0x7f, v71
	v_mad_i64_i32 v[4:5], s[40:41], v0, s96, v[68:69]
	s_lshl_b32 s86, s15, 8
	v_mad_i64_i32 v[6:7], s[40:41], v6, s96, v[68:69]
	v_mad_i64_i32 v[8:9], s[40:41], v8, s96, v[68:69]
	v_mad_i64_i32 v[10:11], s[40:41], v10, s96, v[68:69]
	v_mad_i64_i32 v[12:13], s[40:41], v12, s96, v[68:69]
	v_mad_i64_i32 v[14:15], s[40:41], v14, s96, v[68:69]
	v_mad_i64_i32 v[16:17], s[40:41], v16, s96, v[68:69]
	v_add_u32_e32 v18, s10, v18
	v_lshl_add_u64 v[4:5], v[4:5], 0, s[86:87]
	v_lshlrev_b32_e32 v0, 1, v72
	v_lshl_add_u64 v[6:7], v[6:7], 0, s[86:87]
	v_lshl_add_u64 v[8:9], v[8:9], 0, s[86:87]
	v_lshl_add_u64 v[10:11], v[10:11], 0, s[86:87]
	v_lshl_add_u64 v[12:13], v[12:13], 0, s[86:87]
	v_lshl_add_u64 v[14:15], v[14:15], 0, s[86:87]
	v_lshl_add_u64 v[16:17], v[16:17], 0, s[86:87]
	v_mad_i64_i32 v[18:19], s[40:41], v18, s96, v[68:69]
	v_lshl_add_u64 v[4:5], v[4:5], 0, v[0:1]
	v_lshl_add_u64 v[6:7], v[6:7], 0, v[0:1]
	v_lshl_add_u64 v[8:9], v[8:9], 0, v[0:1]
	v_lshl_add_u64 v[10:11], v[10:11], 0, v[0:1]
	v_lshl_add_u64 v[12:13], v[12:13], 0, v[0:1]
	v_lshl_add_u64 v[14:15], v[14:15], 0, v[0:1]
	v_lshl_add_u64 v[16:17], v[16:17], 0, v[0:1]
	v_lshl_add_u64 v[18:19], v[18:19], 0, s[86:87]
	v_lshl_add_u64 v[18:19], v[18:19], 0, v[0:1]
	global_load_ushort v114, v[4:5], off offset:2048
	global_load_ushort v102, v[6:7], off offset:2048
	global_load_ushort v115, v[8:9], off offset:2048
	global_load_ushort v101, v[10:11], off offset:2048
	global_load_ushort v116, v[12:13], off offset:2048
	global_load_ushort v80, v[14:15], off offset:2048
	global_load_ushort v117, v[16:17], off offset:2048
	global_load_ushort v79, v[18:19], off offset:2048
	v_or_b32_e32 v4, 16, v3
	v_or_b32_e32 v6, 17, v3
	v_or_b32_e32 v8, 18, v3
	v_or_b32_e32 v10, 19, v3
	v_or_b32_e32 v12, 20, v3
	v_or_b32_e32 v14, 21, v3
	v_or_b32_e32 v16, 22, v3
	v_min_i32_e32 v4, 0x101f, v4
	v_min_i32_e32 v6, 0x101f, v6
	v_min_i32_e32 v8, 0x101f, v8
	v_min_i32_e32 v10, 0x101f, v10
	v_min_i32_e32 v12, 0x101f, v12
	v_min_i32_e32 v14, 0x101f, v14
	v_min_i32_e32 v16, 0x101f, v16
	v_or_b32_e32 v18, 23, v3
	v_add_u32_e32 v4, s10, v4
	v_add_u32_e32 v6, s10, v6
	v_add_u32_e32 v8, s10, v8
	v_add_u32_e32 v10, s10, v10
	v_add_u32_e32 v12, s10, v12
	v_add_u32_e32 v14, s10, v14
	v_add_u32_e32 v16, s10, v16
	v_min_i32_e32 v18, 0x101f, v18
	v_mad_i64_i32 v[4:5], s[40:41], v4, s96, v[68:69]
	v_mad_i64_i32 v[6:7], s[40:41], v6, s96, v[68:69]
	v_mad_i64_i32 v[8:9], s[40:41], v8, s96, v[68:69]
	v_mad_i64_i32 v[10:11], s[40:41], v10, s96, v[68:69]
	v_mad_i64_i32 v[12:13], s[40:41], v12, s96, v[68:69]
	v_mad_i64_i32 v[14:15], s[40:41], v14, s96, v[68:69]
	v_mad_i64_i32 v[16:17], s[40:41], v16, s96, v[68:69]
	v_add_u32_e32 v18, s10, v18
	v_lshl_add_u64 v[4:5], v[4:5], 0, s[86:87]
	v_lshl_add_u64 v[6:7], v[6:7], 0, s[86:87]
	v_lshl_add_u64 v[8:9], v[8:9], 0, s[86:87]
	v_lshl_add_u64 v[10:11], v[10:11], 0, s[86:87]
	v_lshl_add_u64 v[12:13], v[12:13], 0, s[86:87]
	v_lshl_add_u64 v[14:15], v[14:15], 0, s[86:87]
	v_lshl_add_u64 v[16:17], v[16:17], 0, s[86:87]
	v_mad_i64_i32 v[18:19], s[40:41], v18, s96, v[68:69]
	v_lshl_add_u64 v[4:5], v[4:5], 0, v[0:1]
	v_lshl_add_u64 v[6:7], v[6:7], 0, v[0:1]
	v_lshl_add_u64 v[8:9], v[8:9], 0, v[0:1]
	v_lshl_add_u64 v[10:11], v[10:11], 0, v[0:1]
	v_lshl_add_u64 v[12:13], v[12:13], 0, v[0:1]
	v_lshl_add_u64 v[14:15], v[14:15], 0, v[0:1]
	v_lshl_add_u64 v[16:17], v[16:17], 0, v[0:1]
	v_lshl_add_u64 v[18:19], v[18:19], 0, s[86:87]
	v_lshl_add_u64 v[18:19], v[18:19], 0, v[0:1]
	global_load_ushort v129, v[4:5], off offset:2048
	global_load_ushort v108, v[6:7], off offset:2048
	global_load_ushort v130, v[8:9], off offset:2048
	global_load_ushort v107, v[10:11], off offset:2048
	global_load_ushort v131, v[12:13], off offset:2048
	global_load_ushort v105, v[14:15], off offset:2048
	global_load_ushort v132, v[16:17], off offset:2048
	global_load_ushort v103, v[18:19], off offset:2048
	v_or_b32_e32 v4, 32, v3
; __device__ __forceinline__ void gla_issue_loads(GlaLoads& L, const bf16_t* proj, int b, int h, int n, int dk, int seg, int t4, bool want_q) {
;     ...
;     for (int q = 0; q < 4; ++q) { const int task = t4 + 256 * q, dv = task & 127, rg = task >> 7;
; #pragma unroll
;         for (int j = 0; j < 8; ++j) { const int rb = n * 64 + rg * 8 + j, rc = rb < TB ? rb : TB - 1; L.vv[q][j] = proj[(size_t)(b * TB + rc) * NPROJ + C_V + h * 128 + dv]; } }
; __device__ void gla3_item(const Params& p, int l, int item, LAS unsigned char* lds) {
;     ...
;     const bf16_t* spT = (const bf16_t*)((const unsigned char*)p.out + OS_KVT) + ((size_t)bh * GCH + n) * 8192;
;     bf16x8 spf[8][2];
; #pragma unroll
;     for (int nt = 0; nt < 8; ++nt)
; #pragma unroll
;         for (int ks = 0; ks < 2; ++ks) spf[nt][ks] = *(const bf16x8*)(spT + (nt * 16 + fr) * 64 + ks * 32 + fq * 8);
;     const int rb = n * 64 + wv * 16 + fr, rbc = rb < TB ? rb : TB - 1;
;     bf16_t* rowp = proj + (size_t)(b * TB + rbc) * NPROJ;
;     u32x2 rwv[8];
; #pragma unroll
;     for (int nt = 0; nt < 8; ++nt) rwv[nt] = *(const u32x2*)(rowp + C_R + h * 128 + nt * 16 + 4 * fq);
;     __syncthreads();
	v_or_b32_e32 v6, 33, v3
	v_or_b32_e32 v8, 34, v3
	v_or_b32_e32 v10, 35, v3
	v_or_b32_e32 v12, 36, v3
	v_or_b32_e32 v14, 37, v3
	v_or_b32_e32 v16, 38, v3
	v_min_i32_e32 v4, 0x101f, v4
	v_min_i32_e32 v6, 0x101f, v6
	v_min_i32_e32 v8, 0x101f, v8
	v_min_i32_e32 v10, 0x101f, v10
	v_min_i32_e32 v12, 0x101f, v12
	v_min_i32_e32 v14, 0x101f, v14
	v_min_i32_e32 v16, 0x101f, v16
	v_or_b32_e32 v18, 39, v3
	v_add_u32_e32 v4, s10, v4
	v_add_u32_e32 v6, s10, v6
	v_add_u32_e32 v8, s10, v8
	v_add_u32_e32 v10, s10, v10
	v_add_u32_e32 v12, s10, v12
	v_add_u32_e32 v14, s10, v14
	v_add_u32_e32 v16, s10, v16
	v_min_i32_e32 v18, 0x101f, v18
	v_mad_i64_i32 v[4:5], s[40:41], v4, s96, v[68:69]
	v_mad_i64_i32 v[6:7], s[40:41], v6, s96, v[68:69]
	v_mad_i64_i32 v[8:9], s[40:41], v8, s96, v[68:69]
	v_mad_i64_i32 v[10:11], s[40:41], v10, s96, v[68:69]
	v_mad_i64_i32 v[12:13], s[40:41], v12, s96, v[68:69]
	v_mad_i64_i32 v[14:15], s[40:41], v14, s96, v[68:69]
	v_mad_i64_i32 v[16:17], s[40:41], v16, s96, v[68:69]
	v_add_u32_e32 v18, s10, v18
	v_lshl_add_u64 v[4:5], v[4:5], 0, s[86:87]
	v_lshl_add_u64 v[6:7], v[6:7], 0, s[86:87]
	v_lshl_add_u64 v[8:9], v[8:9], 0, s[86:87]
	v_lshl_add_u64 v[10:11], v[10:11], 0, s[86:87]
	v_lshl_add_u64 v[12:13], v[12:13], 0, s[86:87]
	v_lshl_add_u64 v[14:15], v[14:15], 0, s[86:87]
	v_lshl_add_u64 v[16:17], v[16:17], 0, s[86:87]
	v_mad_i64_i32 v[18:19], s[40:41], v18, s96, v[68:69]
	v_lshl_add_u64 v[4:5], v[4:5], 0, v[0:1]
	v_lshl_add_u64 v[6:7], v[6:7], 0, v[0:1]
	v_lshl_add_u64 v[8:9], v[8:9], 0, v[0:1]
	v_lshl_add_u64 v[10:11], v[10:11], 0, v[0:1]
	v_lshl_add_u64 v[12:13], v[12:13], 0, v[0:1]
	v_lshl_add_u64 v[14:15], v[14:15], 0, v[0:1]
	v_lshl_add_u64 v[16:17], v[16:17], 0, v[0:1]
	v_lshl_add_u64 v[18:19], v[18:19], 0, s[86:87]
	v_lshl_add_u64 v[18:19], v[18:19], 0, v[0:1]
	global_load_ushort v139, v[4:5], off offset:2048
	global_load_ushort v118, v[6:7], off offset:2048
	global_load_ushort v141, v[8:9], off offset:2048
	global_load_ushort v113, v[10:11], off offset:2048
	global_load_ushort v142, v[12:13], off offset:2048
	global_load_ushort v111, v[14:15], off offset:2048
	global_load_ushort v144, v[16:17], off offset:2048
	global_load_ushort v109, v[18:19], off offset:2048
	v_or_b32_e32 v4, 48, v3
	v_or_b32_e32 v6, 49, v3
	v_or_b32_e32 v8, 50, v3
	v_or_b32_e32 v10, 51, v3
	v_or_b32_e32 v12, 52, v3
	v_or_b32_e32 v14, 53, v3
	v_or_b32_e32 v16, 54, v3
	v_or_b32_e32 v3, 55, v3
	v_min_i32_e32 v4, 0x101f, v4
	v_min_i32_e32 v6, 0x101f, v6
	v_min_i32_e32 v8, 0x101f, v8
	v_min_i32_e32 v10, 0x101f, v10
	v_min_i32_e32 v12, 0x101f, v12
	v_min_i32_e32 v14, 0x101f, v14
	v_min_i32_e32 v16, 0x101f, v16
	v_min_i32_e32 v3, 0x101f, v3
	v_add_u32_e32 v4, s10, v4
	v_add_u32_e32 v6, s10, v6
	v_add_u32_e32 v8, s10, v8
	v_add_u32_e32 v10, s10, v10
	v_add_u32_e32 v12, s10, v12
	v_add_u32_e32 v14, s10, v14
	v_add_u32_e32 v16, s10, v16
	v_add_u32_e32 v3, s10, v3
	v_mad_i64_i32 v[4:5], s[40:41], v4, s96, v[68:69]
	v_mad_i64_i32 v[6:7], s[40:41], v6, s96, v[68:69]
	v_mad_i64_i32 v[8:9], s[40:41], v8, s96, v[68:69]
	v_mad_i64_i32 v[10:11], s[40:41], v10, s96, v[68:69]
	v_mad_i64_i32 v[12:13], s[40:41], v12, s96, v[68:69]
	v_mad_i64_i32 v[14:15], s[40:41], v14, s96, v[68:69]
	v_mad_i64_i32 v[16:17], s[40:41], v16, s96, v[68:69]
	v_mad_i64_i32 v[18:19], s[40:41], v3, s96, v[68:69]
	s_mul_i32 s40, s11, 0x42
	s_mov_b32 s41, s87
	v_ashrrev_i32_e32 v3, 31, v2
	v_lshl_add_u64 v[2:3], v[2:3], 0, s[40:41]
	v_lshl_add_u64 v[4:5], v[4:5], 0, s[86:87]
	v_lshlrev_b64 v[2:3], 14, v[2:3]
	v_and_b32_e32 v75, 15, v71
	v_lshl_add_u64 v[4:5], v[4:5], 0, v[0:1]
	v_lshl_add_u64 v[6:7], v[6:7], 0, s[86:87]
	v_lshl_add_u64 v[8:9], v[8:9], 0, s[86:87]
	v_lshl_add_u64 v[10:11], v[10:11], 0, s[86:87]
	v_lshl_add_u64 v[12:13], v[12:13], 0, s[86:87]
	v_lshl_add_u64 v[14:15], v[14:15], 0, s[86:87]
	v_lshl_add_u64 v[16:17], v[16:17], 0, s[86:87]
	v_lshl_add_u64 v[18:19], v[18:19], 0, s[86:87]
	v_lshl_add_u64 v[2:3], s[16:17], 0, v[2:3]
	v_and_b32_e32 v66, 48, v71
	v_mov_b32_e32 v67, v1
	v_lshl_add_u64 v[6:7], v[6:7], 0, v[0:1]
	v_lshl_add_u64 v[8:9], v[8:9], 0, v[0:1]
	v_lshl_add_u64 v[10:11], v[10:11], 0, v[0:1]
	v_lshl_add_u64 v[12:13], v[12:13], 0, v[0:1]
	v_lshl_add_u64 v[14:15], v[14:15], 0, v[0:1]
	v_lshl_add_u64 v[16:17], v[16:17], 0, v[0:1]
	v_lshl_add_u64 v[18:19], v[18:19], 0, v[0:1]
	global_load_ushort v154, v[4:5], off offset:2048
	global_load_ushort v124, v[6:7], off offset:2048
	global_load_ushort v155, v[8:9], off offset:2048
	global_load_ushort v123, v[10:11], off offset:2048
	global_load_ushort v151, v[12:13], off offset:2048
	global_load_ushort v122, v[14:15], off offset:2048
	global_load_ushort v153, v[16:17], off offset:2048
	global_load_ushort v120, v[18:19], off offset:2048
	v_lshl_add_u64 v[2:3], v[2:3], 0, v[66:67]
	v_lshlrev_b32_e32 v4, 7, v75
	v_mov_b32_e32 v5, v1
	v_lshl_add_u64 v[2:3], v[2:3], 0, v[4:5]
	v_add_co_u32_e32 v4, vcc, s22, v2
	s_movk_i32 s11, 0x2000
	s_nop 0
	v_addc_co_u32_e32 v5, vcc, 0, v3, vcc
	v_add_co_u32_e32 v46, vcc, s11, v2
	s_movk_i32 s11, 0x3000
	s_nop 0
	v_addc_co_u32_e32 v47, vcc, 0, v3, vcc
	global_load_dwordx4 v[58:61], v[2:3], off
	global_load_dwordx4 v[62:65], v[2:3], off offset:64
	global_load_dwordx4 v[50:53], v[2:3], off offset:2048
	global_load_dwordx4 v[54:57], v[2:3], off offset:2112
	v_add_co_u32_e32 v2, vcc, s11, v2
	v_lshl_or_b32 v77, v74, 4, v75
	s_nop 0
	v_addc_co_u32_e32 v3, vcc, 0, v3, vcc
	v_or_b32_e32 v67, v77, v70
	s_movk_i32 s22, 0x1020
	v_cmp_gt_i32_e32 vcc, s22, v67
	v_mov_b32_e32 v82, 0x101f
	v_bfe_u32 v76, v71, 4, 2
	v_cndmask_b32_e32 v67, v82, v67, vcc
	v_add_u32_e32 v67, s10, v67
	v_mad_i64_i32 v[68:69], s[10:11], v67, s96, v[68:69]
	v_lshlrev_b32_e32 v0, 3, v76
	v_lshl_add_u64 v[68:69], v[68:69], 0, s[86:87]
	v_lshl_add_u64 v[82:83], v[68:69], 0, v[0:1]
	global_load_dwordx4 v[42:45], v[4:5], off offset:64
	global_load_dwordx4 v[34:37], v[4:5], off offset:2048
	global_load_dwordx4 v[26:29], v[46:47], off
	global_load_dwordx4 v[30:33], v[46:47], off offset:64
	global_load_dwordx4 v[18:21], v[46:47], off offset:2048
	global_load_dwordx4 v[22:25], v[46:47], off offset:2112
	global_load_dwordx4 v[38:41], v[4:5], off offset:2112
	global_load_dwordx4 v[10:13], v[2:3], off
	global_load_dwordx4 v[14:17], v[2:3], off offset:64
	global_load_dwordx4 v[6:9], v[2:3], off offset:2048
	s_nop 0
	global_load_dwordx4 v[46:49], v[46:47], off offset:-4096
	s_nop 0
	global_load_dwordx4 v[2:5], v[2:3], off offset:2112
	s_nop 0
	global_load_dwordx2 v[98:99], v[82:83], off offset:3072
	global_load_dwordx2 v[96:97], v[82:83], off offset:3104
	global_load_dwordx2 v[94:95], v[82:83], off offset:3136
	global_load_dwordx2 v[92:93], v[82:83], off offset:3168
	global_load_dwordx2 v[90:91], v[82:83], off offset:3200
	global_load_dwordx2 v[88:89], v[82:83], off offset:3232
	global_load_dwordx2 v[86:87], v[82:83], off offset:3264
	global_load_dwordx2 v[84:85], v[82:83], off offset:3296
	s_add_u32 s10, s3, s86
	s_addc_u32 s11, s18, 0
	v_lshlrev_b32_e32 v100, 2, v149
	s_barrier
; #define LAS __attribute__((address_space(3)))
; __device__ __forceinline__ float bf2f(bf16_t b) { return __uint_as_float(((unsigned)b) << 16); }
; __device__ __forceinline__ float logsigmoidf_(float x) { return fminf(x, 0.f) - __logf(1.0f + __expf(-fabsf(x))); }
; __device__ __forceinline__ float gla_cumsum(const Params& p, int l, const GlaLoads& L, int h, int n, int dk, int seg, LAS unsigned char* hl, float (&bc)[16]) {
;     const float ba = p.b_alpha[(size_t)l * 256 + h * 64 + dk]; float run = 0.f;
; #pragma unroll
;     for (int i = 0; i < 16; ++i) { const int rb = n * 64 + seg * 16 + i; const float la = rb < TB ? logsigmoidf_(bf2f(L.xl[i]) + ba) * (1.0f / 16.0f) : 0.f;
;         run += la; bc[i] = run; }
	s_waitcnt vmcnt(56)
	v_mov_b32_e32 v69, v251
	s_movk_i32 s15, 0x1020
	v_cmp_gt_i32_e64 s[40:41], s22, v192
	v_mov_b32_e32 v67, 0
	v_mov_b32_e32 v68, 0
	s_and_saveexec_b64 s[10:11], s[40:41]
	s_cbranch_execz .LBB0_452
	v_lshlrev_b32_e32 v68, 16, v193
	v_add_f32_e32 v68, v69, v68
	s_mov_b32 s22, 0xbfb8aa3b
	v_mul_f32_e64 v192, |v68|, s22
	v_exp_f32_e32 v192, v192
	s_mov_b32 s22, 0x800000
	v_min_f32_e32 v68, 0, v68
	v_add_f32_e32 v192, 1.0, v192
	v_cmp_gt_f32_e64 s[42:43], s22, v192
	s_mov_b32 s22, 0x3f317217
	s_nop 0
	v_cndmask_b32_e64 v193, 0, 32, s[42:43]
	v_ldexp_f32 v192, v192, v193
	v_log_f32_e32 v192, v192
	s_nop 0
	v_mul_f32_e32 v193, 0x3f317217, v192
	v_fma_f32 v193, v192, s22, -v193
	v_fmac_f32_e32 v193, 0x3377d1cf, v192
	s_mov_b32 s22, 0x7f800000
	v_fmac_f32_e32 v193, 0x3f317217, v192
	v_cmp_lt_f32_e64 s[44:45], |v192|, s22
	s_mov_b32 s22, 0x3d800000
	s_nop 0
	v_cndmask_b32_e64 v192, v192, v193, s[44:45]
	v_cndmask_b32_e64 v193, 0, v236, s[42:43]
	v_sub_f32_e32 v192, v192, v193
	v_sub_f32_e32 v68, v68, v192
	v_fma_f32 v68, v68, s22, 0
.LBB0_452:
	s_or_b64 exec, exec, s[10:11]
	v_cmp_gt_i32_e64 s[42:43], s15, v189
	s_and_saveexec_b64 s[10:11], s[42:43]
	s_cbranch_execz .LBB0_454
	v_lshlrev_b32_e32 v67, 16, v191
	v_add_f32_e32 v67, v69, v67
	s_mov_b32 s22, 0xbfb8aa3b
	v_mul_f32_e64 v189, |v67|, s22
	v_exp_f32_e32 v189, v189
	s_mov_b32 s22, 0x800000
	v_min_f32_e32 v67, 0, v67
	v_add_f32_e32 v189, 1.0, v189
	v_cmp_gt_f32_e64 s[44:45], s22, v189
	s_mov_b32 s22, 0x3f317217
	s_nop 0
	v_cndmask_b32_e64 v191, 0, 32, s[44:45]
	v_ldexp_f32 v189, v189, v191
	v_log_f32_e32 v189, v189
	s_nop 0
	v_mul_f32_e32 v191, 0x3f317217, v189
	v_fma_f32 v191, v189, s22, -v191
	v_fmac_f32_e32 v191, 0x3377d1cf, v189
	s_mov_b32 s22, 0x7f800000
	v_fmac_f32_e32 v191, 0x3f317217, v189
	v_cmp_lt_f32_e64 s[46:47], |v189|, s22
	s_nop 1
	v_cndmask_b32_e64 v189, v189, v191, s[46:47]
	v_cndmask_b32_e64 v191, 0, v236, s[44:45]
	v_sub_f32_e32 v189, v189, v191
	v_sub_f32_e32 v67, v67, v189
	v_mul_f32_e32 v67, 0x3d800000, v67
.LBB0_454:
	s_or_b64 exec, exec, s[10:11]
	v_cmp_gt_i32_e64 s[44:45], s15, v188
	v_mov_b32_e32 v188, 0
	v_mov_b32_e32 v189, 0
	s_and_saveexec_b64 s[10:11], s[44:45]
	s_cbranch_execz .LBB0_456
	v_lshlrev_b32_e32 v189, 16, v190
	v_add_f32_e32 v189, v69, v189
	s_mov_b32 s22, 0xbfb8aa3b
	v_mul_f32_e64 v190, |v189|, s22
	v_exp_f32_e32 v190, v190
	s_mov_b32 s22, 0x800000
	v_min_f32_e32 v189, 0, v189
	v_add_f32_e32 v190, 1.0, v190
	v_cmp_gt_f32_e64 s[46:47], s22, v190
	s_mov_b32 s22, 0x3f317217
	s_nop 0
	v_cndmask_b32_e64 v191, 0, 32, s[46:47]
	v_ldexp_f32 v190, v190, v191
	v_log_f32_e32 v190, v190
	s_nop 0
	v_mul_f32_e32 v191, 0x3f317217, v190
	v_fma_f32 v191, v190, s22, -v191
	v_fmac_f32_e32 v191, 0x3377d1cf, v190
	s_mov_b32 s22, 0x7f800000
	v_fmac_f32_e32 v191, 0x3f317217, v190
	v_cmp_lt_f32_e64 s[48:49], |v190|, s22
	s_nop 1
	v_cndmask_b32_e64 v190, v190, v191, s[48:49]
	v_cndmask_b32_e64 v191, 0, v236, s[46:47]
	v_sub_f32_e32 v190, v190, v191
	v_sub_f32_e32 v189, v189, v190
	v_mul_f32_e32 v189, 0x3d800000, v189
.LBB0_456:
	s_or_b64 exec, exec, s[10:11]
	v_cmp_gt_i32_e64 s[46:47], s15, v186
	s_and_saveexec_b64 s[10:11], s[46:47]
	s_cbranch_execz .LBB0_458
	v_lshlrev_b32_e32 v186, 16, v187
	v_add_f32_e32 v186, v69, v186
	s_mov_b32 s22, 0xbfb8aa3b
	v_mul_f32_e64 v187, |v186|, s22
	v_exp_f32_e32 v187, v187
	s_mov_b32 s22, 0x800000
	v_min_f32_e32 v186, 0, v186
	v_add_f32_e32 v187, 1.0, v187
	v_cmp_gt_f32_e64 s[48:49], s22, v187
	s_mov_b32 s22, 0x3f317217
	s_nop 0
	v_cndmask_b32_e64 v188, 0, 32, s[48:49]
	v_ldexp_f32 v187, v187, v188
	v_log_f32_e32 v187, v187
	s_nop 0
	v_mul_f32_e32 v188, 0x3f317217, v187
	v_fma_f32 v188, v187, s22, -v188
	v_fmac_f32_e32 v188, 0x3377d1cf, v187
	s_mov_b32 s22, 0x7f800000
	v_fmac_f32_e32 v188, 0x3f317217, v187
	v_cmp_lt_f32_e64 s[50:51], |v187|, s22
	s_nop 1
	v_cndmask_b32_e64 v187, v187, v188, s[50:51]
	v_cndmask_b32_e64 v188, 0, v236, s[48:49]
	v_sub_f32_e32 v187, v187, v188
	v_sub_f32_e32 v186, v186, v187
	v_mul_f32_e32 v188, 0x3d800000, v186
.LBB0_458:
	s_or_b64 exec, exec, s[10:11]
	v_cmp_gt_i32_e64 s[48:49], s15, v184
	v_mov_b32_e32 v184, 0
	v_mov_b32_e32 v186, 0
	s_and_saveexec_b64 s[10:11], s[48:49]
	s_cbranch_execz .LBB0_460
	v_lshlrev_b32_e32 v185, 16, v185
	v_add_f32_e32 v185, v69, v185
	s_mov_b32 s22, 0xbfb8aa3b
	v_mul_f32_e64 v186, |v185|, s22
	v_exp_f32_e32 v186, v186
	s_mov_b32 s22, 0x800000
	v_min_f32_e32 v185, 0, v185
	v_add_f32_e32 v186, 1.0, v186
	v_cmp_gt_f32_e64 s[50:51], s22, v186
	s_mov_b32 s22, 0x3f317217
	s_nop 0
	v_cndmask_b32_e64 v187, 0, 32, s[50:51]
	v_ldexp_f32 v186, v186, v187
	v_log_f32_e32 v186, v186
	s_nop 0
	v_mul_f32_e32 v187, 0x3f317217, v186
	v_fma_f32 v187, v186, s22, -v187
	v_fmac_f32_e32 v187, 0x3377d1cf, v186
	s_mov_b32 s22, 0x7f800000
	v_fmac_f32_e32 v187, 0x3f317217, v186
	v_cmp_lt_f32_e64 s[52:53], |v186|, s22
	s_nop 1
	v_cndmask_b32_e64 v186, v186, v187, s[52:53]
	v_cndmask_b32_e64 v187, 0, v236, s[50:51]
	v_sub_f32_e32 v186, v186, v187
	v_sub_f32_e32 v185, v185, v186
	v_mul_f32_e32 v186, 0x3d800000, v185
.LBB0_460:
	s_or_b64 exec, exec, s[10:11]
	v_cmp_gt_i32_e64 s[50:51], s15, v182
	s_and_saveexec_b64 s[10:11], s[50:51]
	s_cbranch_execz .LBB0_462
	v_lshlrev_b32_e32 v182, 16, v183
	v_add_f32_e32 v182, v69, v182
	s_mov_b32 s22, 0xbfb8aa3b
	v_mul_f32_e64 v183, |v182|, s22
	v_exp_f32_e32 v183, v183
	s_mov_b32 s22, 0x800000
	v_min_f32_e32 v182, 0, v182
	v_add_f32_e32 v183, 1.0, v183
	v_cmp_gt_f32_e64 s[52:53], s22, v183
	s_mov_b32 s22, 0x3f317217
	s_nop 0
	v_cndmask_b32_e64 v184, 0, 32, s[52:53]
	v_ldexp_f32 v183, v183, v184
	v_log_f32_e32 v183, v183
	s_nop 0
	v_mul_f32_e32 v184, 0x3f317217, v183
	v_fma_f32 v184, v183, s22, -v184
	v_fmac_f32_e32 v184, 0x3377d1cf, v183
	s_mov_b32 s22, 0x7f800000
	v_fmac_f32_e32 v184, 0x3f317217, v183
	v_cmp_lt_f32_e64 s[54:55], |v183|, s22
	s_nop 1
	v_cndmask_b32_e64 v183, v183, v184, s[54:55]
	v_cndmask_b32_e64 v184, 0, v236, s[52:53]
	v_sub_f32_e32 v183, v183, v184
	v_sub_f32_e32 v182, v182, v183
	v_mul_f32_e32 v184, 0x3d800000, v182
; #define LAS __attribute__((address_space(3)))
; __device__ __forceinline__ float bf2f(bf16_t b) { return __uint_as_float(((unsigned)b) << 16); }
; __device__ __forceinline__ float logsigmoidf_(float x) { return fminf(x, 0.f) - __logf(1.0f + __expf(-fabsf(x))); }
; __device__ __forceinline__ float gla_cumsum(const Params& p, int l, const GlaLoads& L, int h, int n, int dk, int seg, LAS unsigned char* hl, float (&bc)[16]) {
;     const float ba = p.b_alpha[(size_t)l * 256 + h * 64 + dk]; float run = 0.f;
; #pragma unroll
;     for (int i = 0; i < 16; ++i) { const int rb = n * 64 + seg * 16 + i; const float la = rb < TB ? logsigmoidf_(bf2f(L.xl[i]) + ba) * (1.0f / 16.0f) : 0.f;
;         run += la; bc[i] = run; }
.LBB0_462:
	s_or_b64 exec, exec, s[10:11]
	v_cmp_gt_i32_e64 s[52:53], s15, v180
	v_mov_b32_e32 v180, 0
	v_mov_b32_e32 v182, 0
	s_and_saveexec_b64 s[10:11], s[52:53]
	s_cbranch_execz .LBB0_464
	v_lshlrev_b32_e32 v181, 16, v181
	v_add_f32_e32 v181, v69, v181
	s_mov_b32 s22, 0xbfb8aa3b
	v_mul_f32_e64 v182, |v181|, s22
	v_exp_f32_e32 v182, v182
	s_mov_b32 s22, 0x800000
	v_min_f32_e32 v181, 0, v181
	v_add_f32_e32 v182, 1.0, v182
	v_cmp_gt_f32_e64 s[54:55], s22, v182
	s_mov_b32 s22, 0x3f317217
	s_nop 0
	v_cndmask_b32_e64 v183, 0, 32, s[54:55]
	v_ldexp_f32 v182, v182, v183
	v_log_f32_e32 v182, v182
	s_nop 0
	v_mul_f32_e32 v183, 0x3f317217, v182
	v_fma_f32 v183, v182, s22, -v183
	v_fmac_f32_e32 v183, 0x3377d1cf, v182
	s_mov_b32 s22, 0x7f800000
	v_fmac_f32_e32 v183, 0x3f317217, v182
	v_cmp_lt_f32_e64 s[56:57], |v182|, s22
	s_nop 1
	v_cndmask_b32_e64 v182, v182, v183, s[56:57]
	v_cndmask_b32_e64 v183, 0, v236, s[54:55]
	v_sub_f32_e32 v182, v182, v183
	v_sub_f32_e32 v181, v181, v182
	v_mul_f32_e32 v182, 0x3d800000, v181
.LBB0_464:
	s_or_b64 exec, exec, s[10:11]
	v_cmp_gt_i32_e64 s[54:55], s15, v178
	s_and_saveexec_b64 s[10:11], s[54:55]
	s_cbranch_execz .LBB0_466
	v_lshlrev_b32_e32 v178, 16, v179
	v_add_f32_e32 v178, v69, v178
	s_mov_b32 s22, 0xbfb8aa3b
	v_mul_f32_e64 v179, |v178|, s22
	v_exp_f32_e32 v179, v179
	s_mov_b32 s22, 0x800000
	v_min_f32_e32 v178, 0, v178
	v_add_f32_e32 v179, 1.0, v179
	v_cmp_gt_f32_e64 s[56:57], s22, v179
	s_mov_b32 s22, 0x3f317217
	s_nop 0
	v_cndmask_b32_e64 v180, 0, 32, s[56:57]
	v_ldexp_f32 v179, v179, v180
	v_log_f32_e32 v179, v179
	s_nop 0
	v_mul_f32_e32 v180, 0x3f317217, v179
	v_fma_f32 v180, v179, s22, -v180
	v_fmac_f32_e32 v180, 0x3377d1cf, v179
	s_mov_b32 s22, 0x7f800000
	v_fmac_f32_e32 v180, 0x3f317217, v179
	v_cmp_lt_f32_e64 s[58:59], |v179|, s22
	s_nop 1
	v_cndmask_b32_e64 v179, v179, v180, s[58:59]
	v_cndmask_b32_e64 v180, 0, v236, s[56:57]
	v_sub_f32_e32 v179, v179, v180
	v_sub_f32_e32 v178, v178, v179
	v_mul_f32_e32 v180, 0x3d800000, v178
.LBB0_466:
	s_or_b64 exec, exec, s[10:11]
	v_cmp_gt_i32_e64 s[56:57], s15, v176
	v_mov_b32_e32 v176, 0
	v_mov_b32_e32 v178, 0
	s_and_saveexec_b64 s[10:11], s[56:57]
	s_cbranch_execz .LBB0_468
	v_lshlrev_b32_e32 v177, 16, v177
	v_add_f32_e32 v177, v69, v177
	s_mov_b32 s22, 0xbfb8aa3b
	v_mul_f32_e64 v178, |v177|, s22
	v_exp_f32_e32 v178, v178
	s_mov_b32 s22, 0x800000
	v_min_f32_e32 v177, 0, v177
	v_add_f32_e32 v178, 1.0, v178
	v_cmp_gt_f32_e64 s[58:59], s22, v178
	s_mov_b32 s22, 0x3f317217
	s_nop 0
	v_cndmask_b32_e64 v179, 0, 32, s[58:59]
	v_ldexp_f32 v178, v178, v179
	v_log_f32_e32 v178, v178
	s_nop 0
	v_mul_f32_e32 v179, 0x3f317217, v178
	v_fma_f32 v179, v178, s22, -v179
	v_fmac_f32_e32 v179, 0x3377d1cf, v178
	s_mov_b32 s22, 0x7f800000
	v_fmac_f32_e32 v179, 0x3f317217, v178
	v_cmp_lt_f32_e64 s[60:61], |v178|, s22
	s_nop 1
	v_cndmask_b32_e64 v178, v178, v179, s[60:61]
	v_cndmask_b32_e64 v179, 0, v236, s[58:59]
	v_sub_f32_e32 v178, v178, v179
	v_sub_f32_e32 v177, v177, v178
	v_mul_f32_e32 v178, 0x3d800000, v177
.LBB0_468:
	s_or_b64 exec, exec, s[10:11]
	v_cmp_gt_i32_e64 s[58:59], s15, v173
	s_and_saveexec_b64 s[10:11], s[58:59]
	s_cbranch_execz .LBB0_470
	v_lshlrev_b32_e32 v173, 16, v175
	v_add_f32_e32 v173, v69, v173
	s_mov_b32 s22, 0xbfb8aa3b
	v_mul_f32_e64 v175, |v173|, s22
	v_exp_f32_e32 v175, v175
	s_mov_b32 s22, 0x800000
	v_min_f32_e32 v173, 0, v173
	v_add_f32_e32 v175, 1.0, v175
	v_cmp_gt_f32_e64 s[60:61], s22, v175
	s_mov_b32 s22, 0x3f317217
	s_nop 0
	v_cndmask_b32_e64 v176, 0, 32, s[60:61]
	v_ldexp_f32 v175, v175, v176
	v_log_f32_e32 v175, v175
	s_nop 0
	v_mul_f32_e32 v176, 0x3f317217, v175
	v_fma_f32 v176, v175, s22, -v176
	v_fmac_f32_e32 v176, 0x3377d1cf, v175
	s_mov_b32 s22, 0x7f800000
	v_fmac_f32_e32 v176, 0x3f317217, v175
	v_cmp_lt_f32_e64 s[62:63], |v175|, s22
	s_nop 1
	v_cndmask_b32_e64 v175, v175, v176, s[62:63]
	v_cndmask_b32_e64 v176, 0, v236, s[60:61]
	v_sub_f32_e32 v175, v175, v176
	v_sub_f32_e32 v173, v173, v175
	v_mul_f32_e32 v176, 0x3d800000, v173
.LBB0_470:
	s_or_b64 exec, exec, s[10:11]
	v_cmp_gt_i32_e64 s[60:61], s15, v172
	v_mov_b32_e32 v172, 0
	v_mov_b32_e32 v173, 0
	s_and_saveexec_b64 s[10:11], s[60:61]
	s_cbranch_execz .LBB0_472
	v_lshlrev_b32_e32 v173, 16, v174
	v_add_f32_e32 v173, v69, v173
	s_mov_b32 s22, 0xbfb8aa3b
	v_mul_f32_e64 v174, |v173|, s22
	v_exp_f32_e32 v174, v174
	s_mov_b32 s22, 0x800000
	v_min_f32_e32 v173, 0, v173
	v_add_f32_e32 v174, 1.0, v174
	v_cmp_gt_f32_e64 s[62:63], s22, v174
	s_mov_b32 s22, 0x3f317217
	s_nop 0
	v_cndmask_b32_e64 v175, 0, 32, s[62:63]
	v_ldexp_f32 v174, v174, v175
	v_log_f32_e32 v174, v174
	s_nop 0
	v_mul_f32_e32 v175, 0x3f317217, v174
	v_fma_f32 v175, v174, s22, -v175
	v_fmac_f32_e32 v175, 0x3377d1cf, v174
	s_mov_b32 s22, 0x7f800000
	v_fmac_f32_e32 v175, 0x3f317217, v174
	v_cmp_lt_f32_e64 s[64:65], |v174|, s22
	s_nop 1
	v_cndmask_b32_e64 v174, v174, v175, s[64:65]
	v_cndmask_b32_e64 v175, 0, v236, s[62:63]
	v_sub_f32_e32 v174, v174, v175
	v_sub_f32_e32 v173, v173, v174
	v_mul_f32_e32 v173, 0x3d800000, v173
; #define LAS __attribute__((address_space(3)))
; __device__ __forceinline__ float bf2f(bf16_t b) { return __uint_as_float(((unsigned)b) << 16); }
; __device__ __forceinline__ float logsigmoidf_(float x) { return fminf(x, 0.f) - __logf(1.0f + __expf(-fabsf(x))); }
; __device__ __forceinline__ float gla_cumsum(const Params& p, int l, const GlaLoads& L, int h, int n, int dk, int seg, LAS unsigned char* hl, float (&bc)[16]) {
;     const float ba = p.b_alpha[(size_t)l * 256 + h * 64 + dk]; float run = 0.f;
; #pragma unroll
;     for (int i = 0; i < 16; ++i) { const int rb = n * 64 + seg * 16 + i; const float la = rb < TB ? logsigmoidf_(bf2f(L.xl[i]) + ba) * (1.0f / 16.0f) : 0.f;
;         run += la; bc[i] = run; }
.LBB0_472:
	s_or_b64 exec, exec, s[10:11]
	v_cmp_gt_i32_e64 s[62:63], s15, v170
	s_and_saveexec_b64 s[10:11], s[62:63]
	s_cbranch_execz .LBB0_474
	v_lshlrev_b32_e32 v170, 16, v171
	v_add_f32_e32 v170, v69, v170
	s_mov_b32 s22, 0xbfb8aa3b
	v_mul_f32_e64 v171, |v170|, s22
	v_exp_f32_e32 v171, v171
	s_mov_b32 s22, 0x800000
	v_min_f32_e32 v170, 0, v170
	v_add_f32_e32 v171, 1.0, v171
	v_cmp_gt_f32_e64 s[64:65], s22, v171
	s_mov_b32 s22, 0x3f317217
	s_nop 0
	v_cndmask_b32_e64 v172, 0, 32, s[64:65]
	v_ldexp_f32 v171, v171, v172
	v_log_f32_e32 v171, v171
	s_nop 0
	v_mul_f32_e32 v172, 0x3f317217, v171
	v_fma_f32 v172, v171, s22, -v172
	v_fmac_f32_e32 v172, 0x3377d1cf, v171
	s_mov_b32 s22, 0x7f800000
	v_fmac_f32_e32 v172, 0x3f317217, v171
	v_cmp_lt_f32_e64 s[66:67], |v171|, s22
	s_nop 1
	v_cndmask_b32_e64 v171, v171, v172, s[66:67]
	v_cndmask_b32_e64 v172, 0, v236, s[64:65]
	v_sub_f32_e32 v171, v171, v172
	v_sub_f32_e32 v170, v170, v171
	v_mul_f32_e32 v172, 0x3d800000, v170
.LBB0_474:
	s_or_b64 exec, exec, s[10:11]
	v_cmp_gt_i32_e64 s[64:65], s15, v168
	v_mov_b32_e32 v174, 0
	v_mov_b32_e32 v175, 0
	s_and_saveexec_b64 s[10:11], s[64:65]
	s_cbranch_execz .LBB0_476
	v_lshlrev_b32_e32 v168, 16, v169
	v_add_f32_e32 v168, v69, v168
	s_mov_b32 s22, 0xbfb8aa3b
	v_mul_f32_e64 v169, |v168|, s22
	v_exp_f32_e32 v169, v169
	s_mov_b32 s22, 0x800000
	v_min_f32_e32 v168, 0, v168
	v_add_f32_e32 v169, 1.0, v169
	v_cmp_gt_f32_e64 s[66:67], s22, v169
	s_mov_b32 s22, 0x3f317217
	s_nop 0
	v_cndmask_b32_e64 v170, 0, 32, s[66:67]
	v_ldexp_f32 v169, v169, v170
	v_log_f32_e32 v169, v169
	s_nop 0
	v_mul_f32_e32 v170, 0x3f317217, v169
	v_fma_f32 v170, v169, s22, -v170
	v_fmac_f32_e32 v170, 0x3377d1cf, v169
	s_mov_b32 s22, 0x7f800000
	v_fmac_f32_e32 v170, 0x3f317217, v169
	v_cmp_lt_f32_e64 s[68:69], |v169|, s22
	s_nop 1
	v_cndmask_b32_e64 v169, v169, v170, s[68:69]
	v_cndmask_b32_e64 v170, 0, v236, s[66:67]
	v_sub_f32_e32 v169, v169, v170
	v_sub_f32_e32 v168, v168, v169
	v_mul_f32_e32 v175, 0x3d800000, v168
.LBB0_476:
	s_or_b64 exec, exec, s[10:11]
	v_cmp_gt_i32_e64 s[66:67], s15, v166
	s_and_saveexec_b64 s[10:11], s[66:67]
	s_cbranch_execz .LBB0_478
	v_lshlrev_b32_e32 v166, 16, v167
	v_add_f32_e32 v166, v69, v166
	s_mov_b32 s22, 0xbfb8aa3b
	v_mul_f32_e64 v167, |v166|, s22
	v_exp_f32_e32 v167, v167
	s_mov_b32 s22, 0x800000
	v_min_f32_e32 v166, 0, v166
	v_add_f32_e32 v167, 1.0, v167
	v_cmp_gt_f32_e64 s[68:69], s22, v167
	s_mov_b32 s22, 0x3f317217
	s_nop 0
	v_cndmask_b32_e64 v168, 0, 32, s[68:69]
	v_ldexp_f32 v167, v167, v168
	v_log_f32_e32 v167, v167
	s_nop 0
	v_mul_f32_e32 v168, 0x3f317217, v167
	v_fma_f32 v168, v167, s22, -v168
	v_fmac_f32_e32 v168, 0x3377d1cf, v167
	s_mov_b32 s22, 0x7f800000
	v_fmac_f32_e32 v168, 0x3f317217, v167
	v_cmp_lt_f32_e64 s[70:71], |v167|, s22
	s_nop 1
	v_cndmask_b32_e64 v167, v167, v168, s[70:71]
	v_cndmask_b32_e64 v168, 0, v236, s[68:69]
	v_sub_f32_e32 v167, v167, v168
	v_sub_f32_e32 v166, v166, v167
	v_mul_f32_e32 v174, 0x3d800000, v166
.LBB0_478:
	s_or_b64 exec, exec, s[10:11]
	v_cmp_gt_i32_e64 s[70:71], s15, v164
	v_mov_b32_e32 v185, 0
	v_mov_b32_e32 v183, 0
	s_and_saveexec_b64 s[10:11], s[70:71]
	s_cbranch_execz .LBB0_480
	v_lshlrev_b32_e32 v164, 16, v165
	v_add_f32_e32 v164, v69, v164
	s_mov_b32 s22, 0xbfb8aa3b
	v_mul_f32_e64 v165, |v164|, s22
	v_exp_f32_e32 v165, v165
	s_mov_b32 s22, 0x800000
	v_min_f32_e32 v164, 0, v164
	v_add_f32_e32 v165, 1.0, v165
	v_cmp_gt_f32_e64 s[68:69], s22, v165
	s_mov_b32 s22, 0x3f317217
	s_nop 0
	v_cndmask_b32_e64 v166, 0, 32, s[68:69]
	v_ldexp_f32 v165, v165, v166
	v_log_f32_e32 v165, v165
	s_nop 0
	v_mul_f32_e32 v166, 0x3f317217, v165
	v_fma_f32 v166, v165, s22, -v166
	v_fmac_f32_e32 v166, 0x3377d1cf, v165
	s_mov_b32 s22, 0x7f800000
	v_fmac_f32_e32 v166, 0x3f317217, v165
	v_cmp_lt_f32_e64 s[74:75], |v165|, s22
	s_nop 1
	v_cndmask_b32_e64 v165, v165, v166, s[74:75]
	v_cndmask_b32_e64 v166, 0, v236, s[68:69]
	v_sub_f32_e32 v165, v165, v166
	v_sub_f32_e32 v164, v164, v165
	v_mul_f32_e32 v183, 0x3d800000, v164
.LBB0_480:
	s_or_b64 exec, exec, s[10:11]
	v_cmp_gt_i32_e64 s[68:69], s15, v162
	s_and_saveexec_b64 s[10:11], s[68:69]
	s_cbranch_execz .LBB0_482
	v_lshlrev_b32_e32 v162, 16, v163
	v_add_f32_e32 v69, v69, v162
	s_mov_b32 s0, 0xbfb8aa3b
	v_mul_f32_e64 v162, |v69|, s0
	v_exp_f32_e32 v162, v162
	s_mov_b32 s0, 0x800000
	v_min_f32_e32 v69, 0, v69
	v_readlane_b32 s97, v253, 45
	v_add_f32_e32 v162, 1.0, v162
	v_cmp_gt_f32_e64 s[74:75], s0, v162
	s_mov_b32 s0, 0x3f317217
	v_readlane_b32 s92, v253, 42
	v_cndmask_b32_e64 v163, 0, 32, s[74:75]
	v_ldexp_f32 v162, v162, v163
	v_log_f32_e32 v162, v162
	s_nop 0
	v_mul_f32_e32 v163, 0x3f317217, v162
	v_fma_f32 v163, v162, s0, -v163
	v_fmac_f32_e32 v163, 0x3377d1cf, v162
	s_mov_b32 s0, 0x7f800000
	v_fmac_f32_e32 v163, 0x3f317217, v162
	v_cmp_lt_f32_e64 s[76:77], |v162|, s0
	v_readlane_b32 s0, v253, 43
	v_readlane_b32 s1, v253, 44
	v_cndmask_b32_e64 v162, v162, v163, s[76:77]
	v_cndmask_b32_e64 v163, 0, v236, s[74:75]
	v_sub_f32_e32 v162, v162, v163
	v_sub_f32_e32 v69, v69, v162
	v_mul_f32_e32 v185, 0x3d800000, v69

; #define LAS __attribute__((address_space(3)))
; __device__ __forceinline__ int otid() { int t = threadIdx.x; asm volatile("" : "+v"(t)); return t; }
; __device__ __forceinline__ void gla_issue_loads(GlaLoads& L, const bf16_t* proj, int b, int h, int n, int dk, int seg, int t4, bool want_q) {
; #pragma unroll
;     for (int i = 0; i < 16; ++i) { const int rb = n * 64 + seg * 16 + i, rc = rb < TB ? rb : TB - 1; const bf16_t* rp = proj + (size_t)(b * TB + rc) * NPROJ + h * 64 + dk;
;         L.xl[i] = rp[C_GL]; L.xk[i] = rp[C_K]; if (want_q) L.xq[i] = rp[C_Q]; }
; __device__ void gla1_item(const Params& p, int l, int item, LAS unsigned char* lds) {
;     const int t = otid(), half = t >> 8, t4 = t & 255, wv = (t >> 6) & 3, lane = t & 63, fr = lane & 15, fq = lane >> 4;
;     const int pair = item % (GCH / 2), bh = item / (GCH / 2), b = bh >> 2, h = bh & 3, n = pair * 2 + half;
;     const bf16_t* proj = (const bf16_t*)(p.ws + WS_PROJ);
;     LAS unsigned char* hl = lds + half * GL_HALF;
;     const int dk = t4 & 63, seg = t4 >> 6;
;     GlaLoads L; gla_issue_loads(L, proj, b, h, n, dk, seg, t4, false);
.LBB0_557:
	s_cmpk_gt_i32 s33, 0x1ff
	s_mov_b64 s[22:23], -1
	s_cbranch_scc0 .LBB0_595
	s_add_i32 s22, s33, 0xfe00
	s_and_b32 s23, s22, 0xffff
	s_mul_i32 s23, s23, 0xf83f
	s_lshr_b32 s97, s23, 21
	s_mul_i32 s30, s97, 33
	s_sub_i32 s22, s22, s30
	s_waitcnt vmcnt(0)
	v_mov_b32_e32 v8, v228
	s_lshl_b32 s22, s22, 1
	s_lshr_b32 s30, s23, 23
	v_ashrrev_i32_e32 v15, 8, v8
	s_bfe_u32 s23, s23, 0x20015
	s_and_b32 s22, s22, 0xfffe
	v_add_u32_e32 v2, s22, v15
	s_mul_i32 s22, s30, 0x1020
	s_lshl_b32 s30, s23, 7
	v_and_b32_e32 v7, 63, v8
	s_lshl_b32 s100, s23, 8
	s_add_u32 s100, s4, s100
	s_addc_u32 s101, s76, 0
	v_lshlrev_b32_e32 v250, 2, v7
	global_load_dword v251, v250, s[100:101]
	s_waitcnt lgkmcnt(0)
	v_bfe_u32 v6, v8, 6, 2
	v_lshlrev_b32_e32 v3, 6, v2
	s_add_u32 s40, s20, s30
	v_lshl_or_b32 v86, v6, 4, v3
	s_addc_u32 s41, s21, 0
	v_lshlrev_b32_e32 v0, 1, v7
	v_lshl_add_u64 v[4:5], s[40:41], 0, v[0:1]
	v_min_i32_e32 v0, 0x101f, v86
	v_add_u32_e32 v0, s22, v0
	v_mad_i64_i32 v[10:11], s[40:41], v0, s96, v[4:5]
	s_movk_i32 s1, 0x1000
	v_or_b32_e32 v89, 1, v86
	v_add_co_u32_e32 v12, vcc, s1, v10
	v_min_i32_e32 v0, 0x101f, v89
	s_nop 0
	v_addc_co_u32_e32 v13, vcc, 0, v11, vcc
	v_add_u32_e32 v0, s22, v0
	global_load_ushort v90, v[12:13], off
	global_load_ushort v9, v[10:11], off offset:1536
	v_mad_i64_i32 v[10:11], s[40:41], v0, s96, v[4:5]
	v_or_b32_e32 v87, 2, v86
	v_add_co_u32_e32 v12, vcc, s1, v10
	v_min_i32_e32 v0, 0x101f, v87
	s_nop 0
	v_addc_co_u32_e32 v13, vcc, 0, v11, vcc
	v_add_u32_e32 v0, s22, v0
	global_load_ushort v88, v[12:13], off
	s_nop 0
	global_load_ushort v10, v[10:11], off offset:1536
	v_mad_i64_i32 v[12:13], s[40:41], v0, s96, v[4:5]
	v_or_b32_e32 v83, 3, v86
	v_add_co_u32_e32 v16, vcc, s1, v12
	v_min_i32_e32 v0, 0x101f, v83
	s_nop 0
	v_addc_co_u32_e32 v17, vcc, 0, v13, vcc
	v_add_u32_e32 v0, s22, v0
	global_load_ushort v85, v[16:17], off
	global_load_ushort v11, v[12:13], off offset:1536
	v_mad_i64_i32 v[12:13], s[40:41], v0, s96, v[4:5]
	v_or_b32_e32 v81, 4, v86
	v_add_co_u32_e32 v16, vcc, s1, v12
	v_min_i32_e32 v0, 0x101f, v81
	s_nop 0
	v_addc_co_u32_e32 v17, vcc, 0, v13, vcc
	v_add_u32_e32 v0, s22, v0
	global_load_ushort v84, v[16:17], off
	s_nop 0
	global_load_ushort v12, v[12:13], off offset:1536
	v_mad_i64_i32 v[16:17], s[40:41], v0, s96, v[4:5]
	v_or_b32_e32 v78, 5, v86
	v_add_co_u32_e32 v18, vcc, s1, v16
	v_min_i32_e32 v0, 0x101f, v78
	s_nop 0
	v_addc_co_u32_e32 v19, vcc, 0, v17, vcc
	v_add_u32_e32 v0, s22, v0
	global_load_ushort v80, v[18:19], off
	global_load_ushort v13, v[16:17], off offset:1536
	v_mad_i64_i32 v[16:17], s[40:41], v0, s96, v[4:5]
	v_or_b32_e32 v74, 6, v86
	v_add_co_u32_e32 v18, vcc, s1, v16
	v_min_i32_e32 v0, 0x101f, v74
	s_nop 0
	v_addc_co_u32_e32 v19, vcc, 0, v17, vcc
	v_add_u32_e32 v0, s22, v0
	global_load_ushort v76, v[18:19], off
	global_load_ushort v14, v[16:17], off offset:1536
	v_mad_i64_i32 v[16:17], s[40:41], v0, s96, v[4:5]
	v_or_b32_e32 v70, 7, v86
	v_add_co_u32_e32 v18, vcc, s1, v16
	v_min_i32_e32 v0, 0x101f, v70
	s_nop 0
	v_addc_co_u32_e32 v19, vcc, 0, v17, vcc
	v_add_u32_e32 v0, s22, v0
	global_load_ushort v73, v[18:19], off
	s_nop 0
	global_load_ushort v16, v[16:17], off offset:1536
	v_mad_i64_i32 v[18:19], s[40:41], v0, s96, v[4:5]
	v_or_b32_e32 v68, 8, v86
	v_add_co_u32_e32 v20, vcc, s1, v18
	v_min_i32_e32 v0, 0x101f, v68
	s_nop 0
	v_addc_co_u32_e32 v21, vcc, 0, v19, vcc
	v_add_u32_e32 v0, s22, v0
	global_load_ushort v71, v[20:21], off
	global_load_ushort v17, v[18:19], off offset:1536
	v_mad_i64_i32 v[18:19], s[40:41], v0, s96, v[4:5]
	v_or_b32_e32 v64, 9, v86
	v_add_co_u32_e32 v20, vcc, s1, v18
	v_min_i32_e32 v0, 0x101f, v64
	s_nop 0
	v_addc_co_u32_e32 v21, vcc, 0, v19, vcc
	v_add_u32_e32 v0, s22, v0
	global_load_ushort v67, v[20:21], off
	s_nop 0
	global_load_ushort v18, v[18:19], off offset:1536
	v_mad_i64_i32 v[20:21], s[40:41], v0, s96, v[4:5]
	v_or_b32_e32 v62, 10, v86
	v_add_co_u32_e32 v22, vcc, s1, v20
	v_min_i32_e32 v0, 0x101f, v62
	s_nop 0
	v_addc_co_u32_e32 v23, vcc, 0, v21, vcc
	v_add_u32_e32 v0, s22, v0
	global_load_ushort v63, v[22:23], off
	global_load_ushort v19, v[20:21], off offset:1536
	v_mad_i64_i32 v[20:21], s[40:41], v0, s96, v[4:5]
	v_or_b32_e32 v57, 11, v86
	v_add_co_u32_e32 v22, vcc, s1, v20
	v_min_i32_e32 v0, 0x101f, v57
	s_nop 0
	v_addc_co_u32_e32 v23, vcc, 0, v21, vcc
	v_add_u32_e32 v0, s22, v0
	global_load_ushort v60, v[22:23], off
	s_nop 0
	global_load_ushort v20, v[20:21], off offset:1536
	v_mad_i64_i32 v[22:23], s[40:41], v0, s96, v[4:5]
	v_or_b32_e32 v55, 12, v86
	v_add_co_u32_e32 v24, vcc, s1, v22
	v_min_i32_e32 v0, 0x101f, v55
	s_nop 0
	v_addc_co_u32_e32 v25, vcc, 0, v23, vcc
	v_add_u32_e32 v0, s22, v0
	global_load_ushort v59, v[24:25], off
	global_load_ushort v21, v[22:23], off offset:1536
	v_mad_i64_i32 v[22:23], s[40:41], v0, s96, v[4:5]
	v_or_b32_e32 v52, 13, v86
	v_add_co_u32_e32 v24, vcc, s1, v22
	v_min_i32_e32 v0, 0x101f, v52
	s_nop 0
	v_addc_co_u32_e32 v25, vcc, 0, v23, vcc
	v_add_u32_e32 v0, s22, v0
	global_load_ushort v54, v[24:25], off
	s_nop 0
	global_load_ushort v22, v[22:23], off offset:1536
	v_mad_i64_i32 v[24:25], s[40:41], v0, s96, v[4:5]
	v_or_b32_e32 v49, 14, v86
	v_add_co_u32_e32 v26, vcc, s1, v24
	v_min_i32_e32 v0, 0x101f, v49
	s_nop 0
	v_addc_co_u32_e32 v27, vcc, 0, v25, vcc
	v_add_u32_e32 v0, s22, v0
	v_or_b32_e32 v44, 15, v86
	global_load_ushort v51, v[26:27], off
	global_load_ushort v23, v[24:25], off offset:1536
	v_mad_i64_i32 v[24:25], s[40:41], v0, s96, v[4:5]
	v_min_i32_e32 v0, 0x101f, v44
	v_add_co_u32_e32 v26, vcc, s1, v24
	v_add_u32_e32 v0, s22, v0
	v_lshrrev_b32_e32 v28, 4, v8
	v_addc_co_u32_e32 v27, vcc, 0, v25, vcc
; __device__ __forceinline__ void gla_issue_loads(GlaLoads& L, const bf16_t* proj, int b, int h, int n, int dk, int seg, int t4, bool want_q) {
; #pragma unroll
;     for (int i = 0; i < 16; ++i) { const int rb = n * 64 + seg * 16 + i, rc = rb < TB ? rb : TB - 1; const bf16_t* rp = proj + (size_t)(b * TB + rc) * NPROJ + h * 64 + dk;
;         L.xl[i] = rp[C_GL]; L.xk[i] = rp[C_K]; if (want_q) L.xq[i] = rp[C_Q]; }
; #pragma unroll
;     for (int q = 0; q < 4; ++q) { const int task = t4 + 256 * q, dv = task & 127, rg = task >> 7;
; #pragma unroll
;         for (int j = 0; j < 8; ++j) { const int rb = n * 64 + rg * 8 + j, rc = rb < TB ? rb : TB - 1; L.vv[q][j] = proj[(size_t)(b * TB + rc) * NPROJ + C_V + h * 128 + dv]; } }
	v_mad_i64_i32 v[4:5], s[40:41], v0, s96, v[4:5]
	global_load_ushort v48, v[26:27], off
	s_nop 0
	global_load_ushort v24, v[24:25], off offset:1536
	v_add_co_u32_e32 v26, vcc, s1, v4
	v_and_or_b32 v43, v28, 8, v3
	s_nop 0
	v_addc_co_u32_e32 v27, vcc, 0, v5, vcc
	v_min_i32_e32 v0, 0x101f, v43
	global_load_ushort v46, v[26:27], off
	s_nop 0
	global_load_ushort v26, v[4:5], off offset:1536
	v_add_u32_e32 v0, s22, v0
	v_mov_b64_e32 v[4:5], s[20:21]
	v_and_b32_e32 v25, 0x7f, v8
	v_mad_i64_i32 v[28:29], s[40:41], v0, s96, v[4:5]
	s_lshl_b32 s86, s23, 8
	v_or_b32_e32 v27, 1, v43
	v_lshl_add_u64 v[28:29], v[28:29], 0, s[86:87]
	v_lshlrev_b32_e32 v0, 1, v25
	v_min_i32_e32 v27, 0x101f, v27
	v_lshl_add_u64 v[28:29], v[28:29], 0, v[0:1]
	v_add_u32_e32 v27, s22, v27
	global_load_ushort v42, v[28:29], off offset:2048
	v_mad_i64_i32 v[28:29], s[40:41], v27, s96, v[4:5]
	v_lshl_add_u64 v[28:29], v[28:29], 0, s[86:87]
	v_lshl_add_u64 v[28:29], v[28:29], 0, v[0:1]
	global_load_ushort v27, v[28:29], off offset:2048
	v_or_b32_e32 v28, 2, v43
	v_min_i32_e32 v28, 0x101f, v28
	v_add_u32_e32 v28, s22, v28
	v_mad_i64_i32 v[28:29], s[40:41], v28, s96, v[4:5]
	v_lshl_add_u64 v[28:29], v[28:29], 0, s[86:87]
	v_lshl_add_u64 v[28:29], v[28:29], 0, v[0:1]
	global_load_ushort v45, v[28:29], off offset:2048
	v_or_b32_e32 v28, 3, v43
	v_min_i32_e32 v28, 0x101f, v28
	v_add_u32_e32 v28, s22, v28
	v_mad_i64_i32 v[28:29], s[40:41], v28, s96, v[4:5]
	v_lshl_add_u64 v[28:29], v[28:29], 0, s[86:87]
	v_lshl_add_u64 v[28:29], v[28:29], 0, v[0:1]
	global_load_ushort v28, v[28:29], off offset:2048
	v_or_b32_e32 v29, 4, v43
	v_min_i32_e32 v29, 0x101f, v29
	v_add_u32_e32 v29, s22, v29
	v_mad_i64_i32 v[30:31], s[40:41], v29, s96, v[4:5]
	v_or_b32_e32 v29, 5, v43
	v_lshl_add_u64 v[30:31], v[30:31], 0, s[86:87]
	v_min_i32_e32 v29, 0x101f, v29
	v_lshl_add_u64 v[30:31], v[30:31], 0, v[0:1]
	v_add_u32_e32 v29, s22, v29
	global_load_ushort v47, v[30:31], off offset:2048
	v_mad_i64_i32 v[30:31], s[40:41], v29, s96, v[4:5]
	v_lshl_add_u64 v[30:31], v[30:31], 0, s[86:87]
	v_lshl_add_u64 v[30:31], v[30:31], 0, v[0:1]
	global_load_ushort v29, v[30:31], off offset:2048
	v_or_b32_e32 v30, 6, v43
	v_min_i32_e32 v30, 0x101f, v30
	v_add_u32_e32 v30, s22, v30
	v_mad_i64_i32 v[30:31], s[40:41], v30, s96, v[4:5]
	v_lshl_add_u64 v[30:31], v[30:31], 0, s[86:87]
	v_lshl_add_u64 v[30:31], v[30:31], 0, v[0:1]
	global_load_ushort v50, v[30:31], off offset:2048
	v_or_b32_e32 v30, 7, v43
	v_min_i32_e32 v30, 0x101f, v30
	v_add_u32_e32 v30, s22, v30
	v_mad_i64_i32 v[30:31], s[40:41], v30, s96, v[4:5]
	v_lshl_add_u64 v[30:31], v[30:31], 0, s[86:87]
	v_lshl_add_u64 v[30:31], v[30:31], 0, v[0:1]
	global_load_ushort v31, v[30:31], off offset:2048
	v_or_b32_e32 v30, 16, v43
	v_min_i32_e32 v30, 0x101f, v30
	v_add_u32_e32 v30, s22, v30
	v_mad_i64_i32 v[32:33], s[40:41], v30, s96, v[4:5]
	v_or_b32_e32 v30, 17, v43
	v_lshl_add_u64 v[32:33], v[32:33], 0, s[86:87]
	v_min_i32_e32 v30, 0x101f, v30
	v_lshl_add_u64 v[32:33], v[32:33], 0, v[0:1]
	v_add_u32_e32 v30, s22, v30
	global_load_ushort v53, v[32:33], off offset:2048
	v_mad_i64_i32 v[32:33], s[40:41], v30, s96, v[4:5]
	v_lshl_add_u64 v[32:33], v[32:33], 0, s[86:87]
	v_lshl_add_u64 v[32:33], v[32:33], 0, v[0:1]
	global_load_ushort v30, v[32:33], off offset:2048
	v_or_b32_e32 v32, 18, v43
	v_min_i32_e32 v32, 0x101f, v32
	v_add_u32_e32 v32, s22, v32
	v_mad_i64_i32 v[32:33], s[40:41], v32, s96, v[4:5]
	v_lshl_add_u64 v[32:33], v[32:33], 0, s[86:87]
	v_lshl_add_u64 v[32:33], v[32:33], 0, v[0:1]
	global_load_ushort v56, v[32:33], off offset:2048
	v_or_b32_e32 v32, 19, v43
	v_min_i32_e32 v32, 0x101f, v32
	v_add_u32_e32 v32, s22, v32
	v_mad_i64_i32 v[32:33], s[40:41], v32, s96, v[4:5]
	v_lshl_add_u64 v[32:33], v[32:33], 0, s[86:87]
	v_lshl_add_u64 v[32:33], v[32:33], 0, v[0:1]
	global_load_ushort v32, v[32:33], off offset:2048
	v_or_b32_e32 v33, 20, v43
	v_min_i32_e32 v33, 0x101f, v33
	v_add_u32_e32 v33, s22, v33
	v_mad_i64_i32 v[34:35], s[40:41], v33, s96, v[4:5]
	v_or_b32_e32 v33, 21, v43
	v_lshl_add_u64 v[34:35], v[34:35], 0, s[86:87]
	v_min_i32_e32 v33, 0x101f, v33
	v_lshl_add_u64 v[34:35], v[34:35], 0, v[0:1]
	v_add_u32_e32 v33, s22, v33
	global_load_ushort v58, v[34:35], off offset:2048
	v_mad_i64_i32 v[34:35], s[40:41], v33, s96, v[4:5]
	v_lshl_add_u64 v[34:35], v[34:35], 0, s[86:87]
	v_lshl_add_u64 v[34:35], v[34:35], 0, v[0:1]
	global_load_ushort v33, v[34:35], off offset:2048
	v_or_b32_e32 v34, 22, v43
	v_min_i32_e32 v34, 0x101f, v34
	v_add_u32_e32 v34, s22, v34
	v_mad_i64_i32 v[34:35], s[40:41], v34, s96, v[4:5]
	v_lshl_add_u64 v[34:35], v[34:35], 0, s[86:87]
	v_lshl_add_u64 v[34:35], v[34:35], 0, v[0:1]
	global_load_ushort v61, v[34:35], off offset:2048
	v_or_b32_e32 v34, 23, v43
	v_min_i32_e32 v34, 0x101f, v34
	v_add_u32_e32 v34, s22, v34
	v_mad_i64_i32 v[34:35], s[40:41], v34, s96, v[4:5]
	v_lshl_add_u64 v[34:35], v[34:35], 0, s[86:87]
	v_lshl_add_u64 v[34:35], v[34:35], 0, v[0:1]
	global_load_ushort v35, v[34:35], off offset:2048
	v_or_b32_e32 v34, 32, v43
	v_min_i32_e32 v34, 0x101f, v34
	v_add_u32_e32 v34, s22, v34
	v_mad_i64_i32 v[36:37], s[40:41], v34, s96, v[4:5]
	v_or_b32_e32 v34, 33, v43
	v_lshl_add_u64 v[36:37], v[36:37], 0, s[86:87]
	v_min_i32_e32 v34, 0x101f, v34
	v_lshl_add_u64 v[36:37], v[36:37], 0, v[0:1]
	v_add_u32_e32 v34, s22, v34
	global_load_ushort v65, v[36:37], off offset:2048
	v_mad_i64_i32 v[36:37], s[40:41], v34, s96, v[4:5]
	v_lshl_add_u64 v[36:37], v[36:37], 0, s[86:87]
	v_lshl_add_u64 v[36:37], v[36:37], 0, v[0:1]
	global_load_ushort v34, v[36:37], off offset:2048
	v_or_b32_e32 v36, 34, v43
	v_min_i32_e32 v36, 0x101f, v36
	v_add_u32_e32 v36, s22, v36
; #define LAS __attribute__((address_space(3)))
; __device__ __forceinline__ float bf2f(bf16_t b) { return __uint_as_float(((unsigned)b) << 16); }
; __device__ __forceinline__ float logsigmoidf_(float x) { return fminf(x, 0.f) - __logf(1.0f + __expf(-fabsf(x))); }
; __device__ __forceinline__ void gla_issue_loads(GlaLoads& L, const bf16_t* proj, int b, int h, int n, int dk, int seg, int t4, bool want_q) {
;     ...
;     for (int q = 0; q < 4; ++q) { const int task = t4 + 256 * q, dv = task & 127, rg = task >> 7;
; #pragma unroll
;         for (int j = 0; j < 8; ++j) { const int rb = n * 64 + rg * 8 + j, rc = rb < TB ? rb : TB - 1; L.vv[q][j] = proj[(size_t)(b * TB + rc) * NPROJ + C_V + h * 128 + dv]; } }
; }
; __device__ __forceinline__ float gla_cumsum(const Params& p, int l, const GlaLoads& L, int h, int n, int dk, int seg, LAS unsigned char* hl, float (&bc)[16]) {
;     const float ba = p.b_alpha[(size_t)l * 256 + h * 64 + dk]; float run = 0.f;
; #pragma unroll
;     for (int i = 0; i < 16; ++i) { const int rb = n * 64 + seg * 16 + i; const float la = rb < TB ? logsigmoidf_(bf2f(L.xl[i]) + ba) * (1.0f / 16.0f) : 0.f;
; __device__ void gla3_item(const Params& p, int l, int item, LAS unsigned char* lds) {
;     ...
;     __syncthreads();
	v_mad_i64_i32 v[36:37], s[40:41], v36, s96, v[4:5]
	v_lshl_add_u64 v[36:37], v[36:37], 0, s[86:87]
	v_lshl_add_u64 v[36:37], v[36:37], 0, v[0:1]
	global_load_ushort v66, v[36:37], off offset:2048
	v_or_b32_e32 v36, 35, v43
	v_min_i32_e32 v36, 0x101f, v36
	v_add_u32_e32 v36, s22, v36
	v_mad_i64_i32 v[36:37], s[40:41], v36, s96, v[4:5]
	v_lshl_add_u64 v[36:37], v[36:37], 0, s[86:87]
	v_lshl_add_u64 v[36:37], v[36:37], 0, v[0:1]
	global_load_ushort v36, v[36:37], off offset:2048
	v_or_b32_e32 v37, 36, v43
	v_min_i32_e32 v37, 0x101f, v37
	v_add_u32_e32 v37, s22, v37
	v_mad_i64_i32 v[38:39], s[40:41], v37, s96, v[4:5]
	v_or_b32_e32 v37, 37, v43
	v_lshl_add_u64 v[38:39], v[38:39], 0, s[86:87]
	v_min_i32_e32 v37, 0x101f, v37
	v_lshl_add_u64 v[38:39], v[38:39], 0, v[0:1]
	v_add_u32_e32 v37, s22, v37
	global_load_ushort v69, v[38:39], off offset:2048
	v_mad_i64_i32 v[38:39], s[40:41], v37, s96, v[4:5]
	v_lshl_add_u64 v[38:39], v[38:39], 0, s[86:87]
	v_lshl_add_u64 v[38:39], v[38:39], 0, v[0:1]
	global_load_ushort v37, v[38:39], off offset:2048
	v_or_b32_e32 v38, 38, v43
	v_min_i32_e32 v38, 0x101f, v38
	v_add_u32_e32 v38, s22, v38
	v_mad_i64_i32 v[38:39], s[40:41], v38, s96, v[4:5]
	v_lshl_add_u64 v[38:39], v[38:39], 0, s[86:87]
	v_lshl_add_u64 v[38:39], v[38:39], 0, v[0:1]
	global_load_ushort v72, v[38:39], off offset:2048
	v_or_b32_e32 v38, 39, v43
	v_min_i32_e32 v38, 0x101f, v38
	v_add_u32_e32 v38, s22, v38
	v_mad_i64_i32 v[38:39], s[40:41], v38, s96, v[4:5]
	v_lshl_add_u64 v[38:39], v[38:39], 0, s[86:87]
	v_lshl_add_u64 v[38:39], v[38:39], 0, v[0:1]
	global_load_ushort v39, v[38:39], off offset:2048
	v_or_b32_e32 v38, 48, v43
	v_min_i32_e32 v38, 0x101f, v38
	v_add_u32_e32 v38, s22, v38
	v_mad_i64_i32 v[40:41], s[40:41], v38, s96, v[4:5]
	v_or_b32_e32 v38, 49, v43
	v_lshl_add_u64 v[40:41], v[40:41], 0, s[86:87]
	v_min_i32_e32 v38, 0x101f, v38
	v_lshl_add_u64 v[40:41], v[40:41], 0, v[0:1]
	v_add_u32_e32 v38, s22, v38
	global_load_ushort v75, v[40:41], off offset:2048
	v_mad_i64_i32 v[40:41], s[40:41], v38, s96, v[4:5]
	v_lshl_add_u64 v[40:41], v[40:41], 0, s[86:87]
	v_lshl_add_u64 v[40:41], v[40:41], 0, v[0:1]
	global_load_ushort v38, v[40:41], off offset:2048
	v_or_b32_e32 v40, 50, v43
	v_min_i32_e32 v40, 0x101f, v40
	v_add_u32_e32 v40, s22, v40
	v_mad_i64_i32 v[40:41], s[40:41], v40, s96, v[4:5]
	v_lshl_add_u64 v[40:41], v[40:41], 0, s[86:87]
	v_lshl_add_u64 v[40:41], v[40:41], 0, v[0:1]
	global_load_ushort v77, v[40:41], off offset:2048
	v_or_b32_e32 v40, 51, v43
	v_min_i32_e32 v40, 0x101f, v40
	v_add_u32_e32 v40, s22, v40
	v_mad_i64_i32 v[40:41], s[40:41], v40, s96, v[4:5]
	v_lshl_add_u64 v[40:41], v[40:41], 0, s[86:87]
	v_lshl_add_u64 v[40:41], v[40:41], 0, v[0:1]
	global_load_ushort v40, v[40:41], off offset:2048
	v_or_b32_e32 v41, 52, v43
	v_min_i32_e32 v41, 0x101f, v41
	v_add_u32_e32 v41, s22, v41
	v_mad_i64_i32 v[92:93], s[40:41], v41, s96, v[4:5]
	v_or_b32_e32 v41, 53, v43
	v_lshl_add_u64 v[92:93], v[92:93], 0, s[86:87]
	v_min_i32_e32 v41, 0x101f, v41
	v_lshl_add_u64 v[92:93], v[92:93], 0, v[0:1]
	v_add_u32_e32 v41, s22, v41
	global_load_ushort v79, v[92:93], off offset:2048
	v_mad_i64_i32 v[92:93], s[40:41], v41, s96, v[4:5]
	v_or_b32_e32 v82, 54, v43
	v_or_b32_e32 v43, 55, v43
	v_lshl_add_u64 v[92:93], v[92:93], 0, s[86:87]
	v_min_i32_e32 v82, 0x101f, v82
	v_min_i32_e32 v43, 0x101f, v43
	v_lshl_add_u64 v[92:93], v[92:93], 0, v[0:1]
	v_add_u32_e32 v82, s22, v82
	v_add_u32_e32 v43, s22, v43
	global_load_ushort v41, v[92:93], off offset:2048
	v_mad_i64_i32 v[92:93], s[40:41], v82, s96, v[4:5]
	v_mad_i64_i32 v[4:5], s[22:23], v43, s96, v[4:5]
	v_lshl_add_u64 v[92:93], v[92:93], 0, s[86:87]
	v_lshl_add_u64 v[4:5], v[4:5], 0, s[86:87]
	s_add_u32 s22, s4, s86
	v_lshl_add_u64 v[92:93], v[92:93], 0, v[0:1]
	v_lshl_add_u64 v[4:5], v[4:5], 0, v[0:1]
	s_addc_u32 s23, s76, 0
	v_lshlrev_b32_e32 v0, 2, v7
	global_load_ushort v82, v[92:93], off offset:2048
	global_load_ushort v43, v[4:5], off offset:2048
	s_barrier
	s_waitcnt vmcnt(32)
	v_mov_b32_e32 v5, v251
	v_cmp_gt_i32_e32 vcc, s0, v86
	v_mov_b32_e32 v4, 0
	v_mov_b32_e32 v86, 0
	s_and_saveexec_b64 s[22:23], vcc
	s_cbranch_execz .LBB0_560
	v_lshlrev_b32_e32 v86, 16, v90
	v_add_f32_e32 v86, v5, v86
	s_mov_b32 s1, 0xbfb8aa3b
	v_mul_f32_e64 v90, |v86|, s1
	v_exp_f32_e32 v90, v90
	s_mov_b32 s1, 0x800000
	v_min_f32_e32 v86, 0, v86
	v_add_f32_e32 v90, 1.0, v90
	v_cmp_gt_f32_e64 s[40:41], s1, v90
	s_mov_b32 s1, 0x3f317217
	s_nop 0
	v_cndmask_b32_e64 v91, 0, 32, s[40:41]
	v_ldexp_f32 v90, v90, v91
	v_log_f32_e32 v90, v90
	s_nop 0
	v_mul_f32_e32 v91, 0x3f317217, v90
	v_fma_f32 v91, v90, s1, -v91
	v_fmac_f32_e32 v91, 0x3377d1cf, v90
	s_mov_b32 s1, 0x7f800000
	v_fmac_f32_e32 v91, 0x3f317217, v90
	v_cmp_lt_f32_e64 s[42:43], |v90|, s1
	s_mov_b32 s1, 0x3d800000
	s_nop 0
	v_cndmask_b32_e64 v90, v90, v91, s[42:43]
	v_cndmask_b32_e64 v91, 0, v236, s[40:41]
	v_sub_f32_e32 v90, v90, v91
	v_sub_f32_e32 v86, v86, v90
	v_fma_f32 v86, v86, s1, 0
.LBB0_560:
	s_or_b64 exec, exec, s[22:23]
	v_cmp_gt_i32_e64 s[40:41], s0, v89
	s_and_saveexec_b64 s[22:23], s[40:41]
	s_cbranch_execz .LBB0_562
	v_lshlrev_b32_e32 v4, 16, v88
	v_add_f32_e32 v4, v5, v4
	s_mov_b32 s1, 0xbfb8aa3b
	v_mul_f32_e64 v88, |v4|, s1
	v_exp_f32_e32 v88, v88
	s_mov_b32 s1, 0x800000
	v_min_f32_e32 v4, 0, v4
	v_add_f32_e32 v88, 1.0, v88
	v_cmp_gt_f32_e64 s[42:43], s1, v88
	s_mov_b32 s1, 0x3f317217
	s_nop 0
	v_cndmask_b32_e64 v89, 0, 32, s[42:43]
	v_ldexp_f32 v88, v88, v89
	v_log_f32_e32 v88, v88
	s_nop 0
	v_mul_f32_e32 v89, 0x3f317217, v88
	v_fma_f32 v89, v88, s1, -v89
	v_fmac_f32_e32 v89, 0x3377d1cf, v88
	s_mov_b32 s1, 0x7f800000
	v_fmac_f32_e32 v89, 0x3f317217, v88
	v_cmp_lt_f32_e64 s[44:45], |v88|, s1
	s_nop 1
	v_cndmask_b32_e64 v88, v88, v89, s[44:45]
	v_cndmask_b32_e64 v89, 0, v236, s[42:43]
	v_sub_f32_e32 v88, v88, v89
	v_sub_f32_e32 v4, v4, v88
	v_mul_f32_e32 v4, 0x3d800000, v4
; __device__ __forceinline__ float bf2f(bf16_t b) { return __uint_as_float(((unsigned)b) << 16); }
; __device__ __forceinline__ float logsigmoidf_(float x) { return fminf(x, 0.f) - __logf(1.0f + __expf(-fabsf(x))); }
; __device__ __forceinline__ float gla_cumsum(const Params& p, int l, const GlaLoads& L, int h, int n, int dk, int seg, LAS unsigned char* hl, float (&bc)[16]) {
;     ...
;     for (int i = 0; i < 16; ++i) { const int rb = n * 64 + seg * 16 + i; const float la = rb < TB ? logsigmoidf_(bf2f(L.xl[i]) + ba) * (1.0f / 16.0f) : 0.f;
;         run += la; bc[i] = run; }
.LBB0_562:
	s_or_b64 exec, exec, s[22:23]
	v_cmp_gt_i32_e64 s[42:43], s0, v87
	v_mov_b32_e32 v87, 0
	v_mov_b32_e32 v88, 0
	s_and_saveexec_b64 s[22:23], s[42:43]
	s_cbranch_execz .LBB0_564
	v_lshlrev_b32_e32 v85, 16, v85
	v_add_f32_e32 v85, v5, v85
	s_mov_b32 s1, 0xbfb8aa3b
	v_mul_f32_e64 v88, |v85|, s1
	v_exp_f32_e32 v88, v88
	s_mov_b32 s1, 0x800000
	v_min_f32_e32 v85, 0, v85
	v_add_f32_e32 v88, 1.0, v88
	v_cmp_gt_f32_e64 s[44:45], s1, v88
	s_mov_b32 s1, 0x3f317217
	s_nop 0
	v_cndmask_b32_e64 v89, 0, 32, s[44:45]
	v_ldexp_f32 v88, v88, v89
	v_log_f32_e32 v88, v88
	s_nop 0
	v_mul_f32_e32 v89, 0x3f317217, v88
	v_fma_f32 v89, v88, s1, -v89
	v_fmac_f32_e32 v89, 0x3377d1cf, v88
	s_mov_b32 s1, 0x7f800000
	v_fmac_f32_e32 v89, 0x3f317217, v88
	v_cmp_lt_f32_e64 s[46:47], |v88|, s1
	s_nop 1
	v_cndmask_b32_e64 v88, v88, v89, s[46:47]
	v_cndmask_b32_e64 v89, 0, v236, s[44:45]
	v_sub_f32_e32 v88, v88, v89
	v_sub_f32_e32 v85, v85, v88
	v_mul_f32_e32 v88, 0x3d800000, v85
.LBB0_564:
	s_or_b64 exec, exec, s[22:23]
	v_cmp_gt_i32_e64 s[44:45], s0, v83
	s_and_saveexec_b64 s[22:23], s[44:45]
	s_cbranch_execz .LBB0_566
	v_lshlrev_b32_e32 v83, 16, v84
	v_add_f32_e32 v83, v5, v83
	s_mov_b32 s1, 0xbfb8aa3b
	v_mul_f32_e64 v84, |v83|, s1
	v_exp_f32_e32 v84, v84
	s_mov_b32 s1, 0x800000
	v_min_f32_e32 v83, 0, v83
	v_add_f32_e32 v84, 1.0, v84
	v_cmp_gt_f32_e64 s[46:47], s1, v84
	s_mov_b32 s1, 0x3f317217
	s_nop 0
	v_cndmask_b32_e64 v85, 0, 32, s[46:47]
	v_ldexp_f32 v84, v84, v85
	v_log_f32_e32 v84, v84
	s_nop 0
	v_mul_f32_e32 v85, 0x3f317217, v84
	v_fma_f32 v85, v84, s1, -v85
	v_fmac_f32_e32 v85, 0x3377d1cf, v84
	s_mov_b32 s1, 0x7f800000
	v_fmac_f32_e32 v85, 0x3f317217, v84
	v_cmp_lt_f32_e64 s[48:49], |v84|, s1
	s_nop 1
	v_cndmask_b32_e64 v84, v84, v85, s[48:49]
	v_cndmask_b32_e64 v85, 0, v236, s[46:47]
	v_sub_f32_e32 v84, v84, v85
	v_sub_f32_e32 v83, v83, v84
	v_mul_f32_e32 v87, 0x3d800000, v83
.LBB0_566:
	s_or_b64 exec, exec, s[22:23]
	v_cmp_gt_i32_e64 s[46:47], s0, v81
	v_mov_b32_e32 v81, 0
	v_mov_b32_e32 v83, 0
	s_and_saveexec_b64 s[22:23], s[46:47]
	s_cbranch_execz .LBB0_568
	v_lshlrev_b32_e32 v80, 16, v80
	v_add_f32_e32 v80, v5, v80
	s_mov_b32 s1, 0xbfb8aa3b
	v_mul_f32_e64 v83, |v80|, s1
	v_exp_f32_e32 v83, v83
	s_mov_b32 s1, 0x800000
	v_min_f32_e32 v80, 0, v80
	v_add_f32_e32 v83, 1.0, v83
	v_cmp_gt_f32_e64 s[48:49], s1, v83
	s_mov_b32 s1, 0x3f317217
	s_nop 0
	v_cndmask_b32_e64 v84, 0, 32, s[48:49]
	v_ldexp_f32 v83, v83, v84
	v_log_f32_e32 v83, v83
	s_nop 0
	v_mul_f32_e32 v84, 0x3f317217, v83
	v_fma_f32 v84, v83, s1, -v84
	v_fmac_f32_e32 v84, 0x3377d1cf, v83
	s_mov_b32 s1, 0x7f800000
	v_fmac_f32_e32 v84, 0x3f317217, v83
	v_cmp_lt_f32_e64 s[50:51], |v83|, s1
	s_nop 1
	v_cndmask_b32_e64 v83, v83, v84, s[50:51]
	v_cndmask_b32_e64 v84, 0, v236, s[48:49]
	v_sub_f32_e32 v83, v83, v84
	v_sub_f32_e32 v80, v80, v83
	v_mul_f32_e32 v83, 0x3d800000, v80
.LBB0_568:
	s_or_b64 exec, exec, s[22:23]
	v_cmp_gt_i32_e64 s[48:49], s0, v78
	s_and_saveexec_b64 s[22:23], s[48:49]
	s_cbranch_execz .LBB0_570
	v_lshlrev_b32_e32 v76, 16, v76
	v_add_f32_e32 v76, v5, v76
	s_mov_b32 s1, 0xbfb8aa3b
	v_mul_f32_e64 v78, |v76|, s1
	v_exp_f32_e32 v78, v78
	s_mov_b32 s1, 0x800000
	v_min_f32_e32 v76, 0, v76
	v_add_f32_e32 v78, 1.0, v78
	v_cmp_gt_f32_e64 s[50:51], s1, v78
	s_mov_b32 s1, 0x3f317217
	s_nop 0
	v_cndmask_b32_e64 v80, 0, 32, s[50:51]
	v_ldexp_f32 v78, v78, v80
	v_log_f32_e32 v78, v78
	s_nop 0
	v_mul_f32_e32 v80, 0x3f317217, v78
	v_fma_f32 v80, v78, s1, -v80
	v_fmac_f32_e32 v80, 0x3377d1cf, v78
	s_mov_b32 s1, 0x7f800000
	v_fmac_f32_e32 v80, 0x3f317217, v78
	v_cmp_lt_f32_e64 s[52:53], |v78|, s1
	s_nop 1
	v_cndmask_b32_e64 v78, v78, v80, s[52:53]
	v_cndmask_b32_e64 v80, 0, v236, s[50:51]
	v_sub_f32_e32 v78, v78, v80
	v_sub_f32_e32 v76, v76, v78
	v_mul_f32_e32 v81, 0x3d800000, v76
.LBB0_570:
	s_or_b64 exec, exec, s[22:23]
	v_cmp_gt_i32_e64 s[50:51], s0, v74
	v_mov_b32_e32 v74, 0
	v_mov_b32_e32 v76, 0
	s_and_saveexec_b64 s[22:23], s[50:51]
	s_cbranch_execz .LBB0_572
	v_lshlrev_b32_e32 v73, 16, v73
	v_add_f32_e32 v73, v5, v73
	s_mov_b32 s1, 0xbfb8aa3b
	v_mul_f32_e64 v76, |v73|, s1
	v_exp_f32_e32 v76, v76
	s_mov_b32 s1, 0x800000
	v_min_f32_e32 v73, 0, v73
	v_add_f32_e32 v76, 1.0, v76
	v_cmp_gt_f32_e64 s[52:53], s1, v76
	s_mov_b32 s1, 0x3f317217
	s_nop 0
	v_cndmask_b32_e64 v78, 0, 32, s[52:53]
	v_ldexp_f32 v76, v76, v78
	v_log_f32_e32 v76, v76
	s_nop 0
	v_mul_f32_e32 v78, 0x3f317217, v76
	v_fma_f32 v78, v76, s1, -v78
	v_fmac_f32_e32 v78, 0x3377d1cf, v76
	s_mov_b32 s1, 0x7f800000
	v_fmac_f32_e32 v78, 0x3f317217, v76
	v_cmp_lt_f32_e64 s[54:55], |v76|, s1
	s_nop 1
	v_cndmask_b32_e64 v76, v76, v78, s[54:55]
	v_cndmask_b32_e64 v78, 0, v236, s[52:53]
	v_sub_f32_e32 v76, v76, v78
	v_sub_f32_e32 v73, v73, v76
	v_mul_f32_e32 v76, 0x3d800000, v73
.LBB0_572:
	s_or_b64 exec, exec, s[22:23]
	v_cmp_gt_i32_e64 s[52:53], s0, v70
	s_and_saveexec_b64 s[22:23], s[52:53]
	s_cbranch_execz .LBB0_574
	v_lshlrev_b32_e32 v70, 16, v71
	v_add_f32_e32 v70, v5, v70
	s_mov_b32 s1, 0xbfb8aa3b
	v_mul_f32_e64 v71, |v70|, s1
	v_exp_f32_e32 v71, v71
	s_mov_b32 s1, 0x800000
	v_min_f32_e32 v70, 0, v70
	v_add_f32_e32 v71, 1.0, v71
	v_cmp_gt_f32_e64 s[54:55], s1, v71
	s_mov_b32 s1, 0x3f317217
	s_nop 0
	v_cndmask_b32_e64 v73, 0, 32, s[54:55]
	v_ldexp_f32 v71, v71, v73
	v_log_f32_e32 v71, v71
	s_nop 0
	v_mul_f32_e32 v73, 0x3f317217, v71
	v_fma_f32 v73, v71, s1, -v73
	v_fmac_f32_e32 v73, 0x3377d1cf, v71
	s_mov_b32 s1, 0x7f800000
	v_fmac_f32_e32 v73, 0x3f317217, v71
	v_cmp_lt_f32_e64 s[56:57], |v71|, s1
	s_nop 1
	v_cndmask_b32_e64 v71, v71, v73, s[56:57]
	v_cndmask_b32_e64 v73, 0, v236, s[54:55]
	v_sub_f32_e32 v71, v71, v73
	v_sub_f32_e32 v70, v70, v71
	v_mul_f32_e32 v74, 0x3d800000, v70
; __device__ __forceinline__ float bf2f(bf16_t b) { return __uint_as_float(((unsigned)b) << 16); }
; __device__ __forceinline__ float logsigmoidf_(float x) { return fminf(x, 0.f) - __logf(1.0f + __expf(-fabsf(x))); }
; __device__ __forceinline__ float gla_cumsum(const Params& p, int l, const GlaLoads& L, int h, int n, int dk, int seg, LAS unsigned char* hl, float (&bc)[16]) {
;     ...
;     for (int i = 0; i < 16; ++i) { const int rb = n * 64 + seg * 16 + i; const float la = rb < TB ? logsigmoidf_(bf2f(L.xl[i]) + ba) * (1.0f / 16.0f) : 0.f;
;         run += la; bc[i] = run; }
.LBB0_574:
	s_or_b64 exec, exec, s[22:23]
	v_cmp_gt_i32_e64 s[54:55], s0, v68
	v_mov_b32_e32 v68, 0
	v_mov_b32_e32 v70, 0
	s_and_saveexec_b64 s[22:23], s[54:55]
	s_cbranch_execz .LBB0_576
	v_lshlrev_b32_e32 v67, 16, v67
	v_add_f32_e32 v67, v5, v67
	s_mov_b32 s1, 0xbfb8aa3b
	v_mul_f32_e64 v70, |v67|, s1
	v_exp_f32_e32 v70, v70
	s_mov_b32 s1, 0x800000
	v_min_f32_e32 v67, 0, v67
	v_add_f32_e32 v70, 1.0, v70
	v_cmp_gt_f32_e64 s[56:57], s1, v70
	s_mov_b32 s1, 0x3f317217
	s_nop 0
	v_cndmask_b32_e64 v71, 0, 32, s[56:57]
	v_ldexp_f32 v70, v70, v71
	v_log_f32_e32 v70, v70
	s_nop 0
	v_mul_f32_e32 v71, 0x3f317217, v70
	v_fma_f32 v71, v70, s1, -v71
	v_fmac_f32_e32 v71, 0x3377d1cf, v70
	s_mov_b32 s1, 0x7f800000
	v_fmac_f32_e32 v71, 0x3f317217, v70
	v_cmp_lt_f32_e64 s[58:59], |v70|, s1
	s_nop 1
	v_cndmask_b32_e64 v70, v70, v71, s[58:59]
	v_cndmask_b32_e64 v71, 0, v236, s[56:57]
	v_sub_f32_e32 v70, v70, v71
	v_sub_f32_e32 v67, v67, v70
	v_mul_f32_e32 v70, 0x3d800000, v67
.LBB0_576:
	s_or_b64 exec, exec, s[22:23]
	v_cmp_gt_i32_e64 s[56:57], s0, v64
	s_and_saveexec_b64 s[22:23], s[56:57]
	s_cbranch_execz .LBB0_578
	v_lshlrev_b32_e32 v63, 16, v63
	v_add_f32_e32 v63, v5, v63
	s_mov_b32 s1, 0xbfb8aa3b
	v_mul_f32_e64 v64, |v63|, s1
	v_exp_f32_e32 v64, v64
	s_mov_b32 s1, 0x800000
	v_min_f32_e32 v63, 0, v63
	v_add_f32_e32 v64, 1.0, v64
	v_cmp_gt_f32_e64 s[58:59], s1, v64
	s_mov_b32 s1, 0x3f317217
	s_nop 0
	v_cndmask_b32_e64 v67, 0, 32, s[58:59]
	v_ldexp_f32 v64, v64, v67
	v_log_f32_e32 v64, v64
	s_nop 0
	v_mul_f32_e32 v67, 0x3f317217, v64
	v_fma_f32 v67, v64, s1, -v67
	v_fmac_f32_e32 v67, 0x3377d1cf, v64
	s_mov_b32 s1, 0x7f800000
	v_fmac_f32_e32 v67, 0x3f317217, v64
	v_cmp_lt_f32_e64 s[60:61], |v64|, s1
	s_nop 1
	v_cndmask_b32_e64 v64, v64, v67, s[60:61]
	v_cndmask_b32_e64 v67, 0, v236, s[58:59]
	v_sub_f32_e32 v64, v64, v67
	v_sub_f32_e32 v63, v63, v64
	v_mul_f32_e32 v68, 0x3d800000, v63
.LBB0_578:
	s_or_b64 exec, exec, s[22:23]
	v_cmp_gt_i32_e64 s[58:59], s0, v62
	v_mov_b32_e32 v62, 0
	v_mov_b32_e32 v63, 0
	s_and_saveexec_b64 s[22:23], s[58:59]
	s_cbranch_execz .LBB0_580
	v_lshlrev_b32_e32 v60, 16, v60
	v_add_f32_e32 v60, v5, v60
	s_mov_b32 s1, 0xbfb8aa3b
	v_mul_f32_e64 v63, |v60|, s1
	v_exp_f32_e32 v63, v63
	s_mov_b32 s1, 0x800000
	v_min_f32_e32 v60, 0, v60
	v_add_f32_e32 v63, 1.0, v63
	v_cmp_gt_f32_e64 s[60:61], s1, v63
	s_mov_b32 s1, 0x3f317217
	s_nop 0
	v_cndmask_b32_e64 v64, 0, 32, s[60:61]
	v_ldexp_f32 v63, v63, v64
	v_log_f32_e32 v63, v63
	s_nop 0
	v_mul_f32_e32 v64, 0x3f317217, v63
	v_fma_f32 v64, v63, s1, -v64
	v_fmac_f32_e32 v64, 0x3377d1cf, v63
	s_mov_b32 s1, 0x7f800000
	v_fmac_f32_e32 v64, 0x3f317217, v63
	v_cmp_lt_f32_e64 s[62:63], |v63|, s1
	s_nop 1
	v_cndmask_b32_e64 v63, v63, v64, s[62:63]
	v_cndmask_b32_e64 v64, 0, v236, s[60:61]
	v_sub_f32_e32 v63, v63, v64
	v_sub_f32_e32 v60, v60, v63
	v_mul_f32_e32 v63, 0x3d800000, v60
.LBB0_580:
	s_or_b64 exec, exec, s[22:23]
	v_cmp_gt_i32_e64 s[60:61], s0, v57
	s_and_saveexec_b64 s[22:23], s[60:61]
	s_cbranch_execz .LBB0_582
	v_lshlrev_b32_e32 v57, 16, v59
	v_add_f32_e32 v57, v5, v57
	s_mov_b32 s1, 0xbfb8aa3b
	v_mul_f32_e64 v59, |v57|, s1
	v_exp_f32_e32 v59, v59
	s_mov_b32 s1, 0x800000
	v_min_f32_e32 v57, 0, v57
	v_add_f32_e32 v59, 1.0, v59
	v_cmp_gt_f32_e64 s[62:63], s1, v59
	s_mov_b32 s1, 0x3f317217
	s_nop 0
	v_cndmask_b32_e64 v60, 0, 32, s[62:63]
	v_ldexp_f32 v59, v59, v60
	v_log_f32_e32 v59, v59
	s_nop 0
	v_mul_f32_e32 v60, 0x3f317217, v59
	v_fma_f32 v60, v59, s1, -v60
	v_fmac_f32_e32 v60, 0x3377d1cf, v59
	s_mov_b32 s1, 0x7f800000
	v_fmac_f32_e32 v60, 0x3f317217, v59
	v_cmp_lt_f32_e64 s[64:65], |v59|, s1
	s_nop 1
	v_cndmask_b32_e64 v59, v59, v60, s[64:65]
	v_cndmask_b32_e64 v60, 0, v236, s[62:63]
	v_sub_f32_e32 v59, v59, v60
	v_sub_f32_e32 v57, v57, v59
	v_mul_f32_e32 v62, 0x3d800000, v57
.LBB0_582:
	s_or_b64 exec, exec, s[22:23]
	v_cmp_gt_i32_e64 s[62:63], s0, v55
	v_mov_b32_e32 v55, 0
	v_mov_b32_e32 v57, 0
	s_and_saveexec_b64 s[22:23], s[62:63]
	s_cbranch_execz .LBB0_584
	v_lshlrev_b32_e32 v54, 16, v54
	v_add_f32_e32 v54, v5, v54
	s_mov_b32 s1, 0xbfb8aa3b
	v_mul_f32_e64 v57, |v54|, s1
	v_exp_f32_e32 v57, v57
	s_mov_b32 s1, 0x800000
	v_min_f32_e32 v54, 0, v54
	v_add_f32_e32 v57, 1.0, v57
	v_cmp_gt_f32_e64 s[64:65], s1, v57
	s_mov_b32 s1, 0x3f317217
	s_nop 0
	v_cndmask_b32_e64 v59, 0, 32, s[64:65]
	v_ldexp_f32 v57, v57, v59
	v_log_f32_e32 v57, v57
	s_nop 0
	v_mul_f32_e32 v59, 0x3f317217, v57
	v_fma_f32 v59, v57, s1, -v59
	v_fmac_f32_e32 v59, 0x3377d1cf, v57
	s_mov_b32 s1, 0x7f800000
	v_fmac_f32_e32 v59, 0x3f317217, v57
	v_cmp_lt_f32_e64 s[66:67], |v57|, s1
	s_nop 1
	v_cndmask_b32_e64 v57, v57, v59, s[66:67]
	v_cndmask_b32_e64 v59, 0, v236, s[64:65]
	v_sub_f32_e32 v57, v57, v59
	v_sub_f32_e32 v54, v54, v57
	v_mul_f32_e32 v57, 0x3d800000, v54
.LBB0_584:
	s_or_b64 exec, exec, s[22:23]
	v_cmp_gt_i32_e64 s[66:67], s0, v52
	s_and_saveexec_b64 s[22:23], s[66:67]
	s_cbranch_execz .LBB0_586
	v_lshlrev_b32_e32 v51, 16, v51
	v_add_f32_e32 v51, v5, v51
	s_mov_b32 s1, 0xbfb8aa3b
	v_mul_f32_e64 v52, |v51|, s1
	v_exp_f32_e32 v52, v52
	s_mov_b32 s1, 0x800000
	v_min_f32_e32 v51, 0, v51
	v_add_f32_e32 v52, 1.0, v52
	v_cmp_gt_f32_e64 s[64:65], s1, v52
	s_mov_b32 s1, 0x3f317217
	s_nop 0
	v_cndmask_b32_e64 v54, 0, 32, s[64:65]
	v_ldexp_f32 v52, v52, v54
	v_log_f32_e32 v52, v52
	s_nop 0
	v_mul_f32_e32 v54, 0x3f317217, v52
	v_fma_f32 v54, v52, s1, -v54
	v_fmac_f32_e32 v54, 0x3377d1cf, v52
	s_mov_b32 s1, 0x7f800000
	v_fmac_f32_e32 v54, 0x3f317217, v52
	v_cmp_lt_f32_e64 s[68:69], |v52|, s1
	s_nop 1
	v_cndmask_b32_e64 v52, v52, v54, s[68:69]
	v_cndmask_b32_e64 v54, 0, v236, s[64:65]
	v_sub_f32_e32 v52, v52, v54
	v_sub_f32_e32 v51, v51, v52
	v_mul_f32_e32 v55, 0x3d800000, v51
; #define LAS __attribute__((address_space(3)))
; __device__ __forceinline__ float bf2f(bf16_t b) { return __uint_as_float(((unsigned)b) << 16); }
; __device__ __forceinline__ unsigned cvt_pk_bf16(float lo, float hi) { const f32x2 f = {lo, hi}; const bf16n2 v = __builtin_convertvector(f, bf16n2); return __builtin_bit_cast(unsigned, v); }
; __device__ __forceinline__ float gla_cumsum(const Params& p, int l, const GlaLoads& L, int h, int n, int dk, int seg, LAS unsigned char* hl, float (&bc)[16]) {
;     ...
;         run += la; bc[i] = run; }
;     LAS float* segs = (LAS float*)(hl + GL_SEG);
;     segs[seg * 64 + dk] = run;
;     __syncthreads();
;     float pre = 0.f, tot = 0.f;
; #pragma unroll
;     for (int s = 0; s < 4; ++s) { const float v = segs[s * 64 + dk]; tot += v; if (s < seg) pre += v; }
; #pragma unroll
;     for (int i = 0; i < 16; ++i) bc[i] += pre;
; __device__ void gla1_item(const Params& p, int l, int item, LAS unsigned char* lds) {
;     ...
;     { unsigned w[8];
; #pragma unroll
;       for (int i = 0; i < 16; i += 2) { const int rb = n * 64 + seg * 16 + i;
;           const float k0 = rb < TB ? bf2f(L.xk[i]) * __expf(tot - bc[i]) : 0.f, k1 = rb + 1 < TB ? bf2f(L.xk[i + 1]) * __expf(tot - bc[i + 1]) : 0.f;
;           w[i >> 1] = cvt_pk_bf16(k0, k1); }
;       *(LAS u32x4*)(hl + GL_KI + dk * 144 + seg * 32) = (u32x4){w[0], w[1], w[2], w[3]};
;       *(LAS u32x4*)(hl + GL_KI + dk * 144 + seg * 32 + 16) = (u32x4){w[4], w[5], w[6], w[7]}; }
.LBB0_586:
	s_or_b64 exec, exec, s[22:23]
	v_cmp_gt_i32_e64 s[68:69], s0, v49
	v_mov_b32_e32 v49, 0
	v_mov_b32_e32 v51, 0
	s_and_saveexec_b64 s[22:23], s[68:69]
	s_cbranch_execz .LBB0_588
	v_lshlrev_b32_e32 v48, 16, v48
	v_add_f32_e32 v48, v5, v48
	s_mov_b32 s1, 0xbfb8aa3b
	v_mul_f32_e64 v51, |v48|, s1
	v_exp_f32_e32 v51, v51
	s_mov_b32 s1, 0x800000
	v_min_f32_e32 v48, 0, v48
	v_add_f32_e32 v51, 1.0, v51
	v_cmp_gt_f32_e64 s[64:65], s1, v51
	s_mov_b32 s1, 0x3f317217
	s_nop 0
	v_cndmask_b32_e64 v52, 0, 32, s[64:65]
	v_ldexp_f32 v51, v51, v52
	v_log_f32_e32 v51, v51
	s_nop 0
	v_mul_f32_e32 v52, 0x3f317217, v51
	v_fma_f32 v52, v51, s1, -v52
	v_fmac_f32_e32 v52, 0x3377d1cf, v51
	s_mov_b32 s1, 0x7f800000
	v_fmac_f32_e32 v52, 0x3f317217, v51
	v_cmp_lt_f32_e64 s[70:71], |v51|, s1
	s_nop 1
	v_cndmask_b32_e64 v51, v51, v52, s[70:71]
	v_cndmask_b32_e64 v52, 0, v236, s[64:65]
	v_sub_f32_e32 v51, v51, v52
	v_sub_f32_e32 v48, v48, v51
	v_mul_f32_e32 v51, 0x3d800000, v48
.LBB0_588:
	s_or_b64 exec, exec, s[22:23]
	v_cmp_gt_i32_e64 s[70:71], s0, v44
	s_and_saveexec_b64 s[22:23], s[70:71]
	s_cbranch_execz .LBB0_590
	v_lshlrev_b32_e32 v44, 16, v46
	v_add_f32_e32 v5, v5, v44
	s_mov_b32 s1, 0xbfb8aa3b
	v_mul_f32_e64 v44, |v5|, s1
	v_exp_f32_e32 v44, v44
	s_mov_b32 s1, 0x800000
	v_min_f32_e32 v5, 0, v5
	v_add_f32_e32 v44, 1.0, v44
	v_cmp_gt_f32_e64 s[64:65], s1, v44
	s_mov_b32 s1, 0x3f317217
	s_nop 0
	v_cndmask_b32_e64 v46, 0, 32, s[64:65]
	v_ldexp_f32 v44, v44, v46
	v_log_f32_e32 v44, v44
	s_nop 0
	v_mul_f32_e32 v46, 0x3f317217, v44
	v_fma_f32 v46, v44, s1, -v46
	v_fmac_f32_e32 v46, 0x3377d1cf, v44
	s_mov_b32 s1, 0x7f800000
	v_fmac_f32_e32 v46, 0x3f317217, v44
	v_cmp_lt_f32_e64 s[74:75], |v44|, s1
	s_nop 1
	v_cndmask_b32_e64 v44, v44, v46, s[74:75]
	v_cndmask_b32_e64 v46, 0, v236, s[64:65]
	v_sub_f32_e32 v44, v44, v46
	v_sub_f32_e32 v5, v5, v44
	v_mul_f32_e32 v49, 0x3d800000, v5
.LBB0_590:
	s_or_b64 exec, exec, s[22:23]
	v_add_f32_e32 v4, v86, v4
	v_add_f32_e32 v48, v4, v88
	v_add_f32_e32 v52, v48, v87
	v_add_f32_e32 v54, v52, v83
	v_add_f32_e32 v59, v54, v81
	v_add_f32_e32 v60, v59, v76
	v_add_f32_e32 v64, v60, v74
	v_add_f32_e32 v67, v64, v70
	v_add_f32_e32 v68, v67, v68
	v_add_f32_e32 v63, v68, v63
	v_add_f32_e32 v62, v63, v62
	s_waitcnt vmcnt(0)
	v_mul_i32_i24_e32 v5, 0xb800, v15
	v_add_f32_e32 v57, v62, v57
	v_add_f32_e32 v55, v57, v55
	v_add_u32_e32 v15, 0, v5
	v_add_f32_e32 v51, v55, v51
	v_lshl_add_u32 v46, v7, 2, v15
	v_lshl_add_u32 v44, v6, 8, v46
	v_add_f32_e32 v5, v51, v49
	v_and_b32_e32 v70, 0xffff, v45
	ds_write_b32 v44, v5 offset:46080
	s_waitcnt lgkmcnt(0)
	s_barrier
	ds_read2st64_b32 v[44:45], v46 offset0:180 offset1:181
	v_and_b32_e32 v71, 0xffff, v47
	ds_read2st64_b32 v[46:47], v46 offset0:182 offset1:183
	v_cmp_gt_u32_sdwa s[64:65], v8, v237 src0_sel:BYTE_0 src1_sel:DWORD
	s_movk_i32 s1, 0x7f
	s_waitcnt lgkmcnt(1)
	v_add_f32_e32 v44, 0, v44
	v_cndmask_b32_e64 v49, 0, v44, s[64:65]
	v_and_b32_e32 v74, 0xffff, v77
	v_add_f32_e32 v77, v45, v49
	v_cmp_gt_u32_sdwa s[74:75], v8, s1 src0_sel:BYTE_0 src1_sel:DWORD
	v_lshlrev_b32_e32 v9, 16, v9
	v_lshlrev_b32_e32 v10, 16, v10
	v_cndmask_b32_e64 v49, v49, v77, s[74:75]
	s_waitcnt lgkmcnt(0)
	v_add_f32_e32 v77, v46, v49
	v_cmp_eq_u32_e64 s[74:75], 3, v6
	v_lshlrev_b32_e32 v6, 5, v6
	v_and_b32_e32 v42, 0xffff, v42
	v_cndmask_b32_e64 v49, v49, v77, s[74:75]
	v_add_f32_e32 v77, v4, v49
	v_add_f32_e32 v4, v44, v45
	v_add_f32_e32 v78, v48, v49
	v_add_f32_e32 v4, v4, v46
	v_mov_b32_e32 v48, v47
	v_pk_add_f32 v[4:5], v[4:5], v[48:49]
	v_add_f32_e32 v44, v86, v49
	v_sub_f32_e32 v44, v4, v44
	v_sub_f32_e32 v45, v4, v77
	v_mul_f32_e32 v44, 0x3fb8aa3b, v44
	v_mul_f32_e32 v45, 0x3fb8aa3b, v45
	v_exp_f32_e32 v44, v44
	v_exp_f32_e32 v45, v45
	v_add_f32_e32 v52, v52, v49
	v_add_f32_e32 v54, v54, v49
	v_mul_f32_e32 v9, v44, v9
	v_mul_f32_e32 v10, v45, v10
	v_cndmask_b32_e32 v9, 0, v9, vcc
	v_cndmask_b32_e64 v10, 0, v10, s[40:41]
	v_cvt_pk_bf16_f32 v10, v9, v10
	v_lshlrev_b32_e32 v9, 16, v11
	v_sub_f32_e32 v11, v4, v78
	v_mul_f32_e32 v11, 0x3fb8aa3b, v11
	v_sub_f32_e32 v44, v4, v52
	v_exp_f32_e32 v11, v11
	v_mul_f32_e32 v44, 0x3fb8aa3b, v44
	v_exp_f32_e32 v44, v44
	v_add_f32_e32 v59, v59, v49
	v_mul_f32_e32 v9, v11, v9
	v_lshlrev_b32_e32 v11, 16, v12
	v_mul_f32_e32 v11, v44, v11
	v_cndmask_b32_e64 v9, 0, v9, s[42:43]
	v_cndmask_b32_e64 v11, 0, v11, s[44:45]
	v_sub_f32_e32 v12, v4, v54
	v_cvt_pk_bf16_f32 v11, v9, v11
	v_lshlrev_b32_e32 v9, 16, v13
	v_mul_f32_e32 v12, 0x3fb8aa3b, v12
	v_sub_f32_e32 v13, v4, v59
	v_exp_f32_e32 v12, v12
	v_mul_f32_e32 v13, 0x3fb8aa3b, v13
	v_exp_f32_e32 v13, v13
	v_add_f32_e32 v60, v60, v49
	v_mul_f32_e32 v9, v12, v9
	v_lshlrev_b32_e32 v12, 16, v14
	v_add_f32_e32 v64, v64, v49
	v_mul_f32_e32 v12, v13, v12
	v_sub_f32_e32 v13, v4, v60
	v_mul_f32_e32 v13, 0x3fb8aa3b, v13
	v_sub_f32_e32 v14, v4, v64
	v_exp_f32_e32 v13, v13
	v_mul_f32_e32 v14, 0x3fb8aa3b, v14
	v_exp_f32_e32 v14, v14
	v_cndmask_b32_e64 v9, 0, v9, s[46:47]
	v_cndmask_b32_e64 v12, 0, v12, s[48:49]
	v_cvt_pk_bf16_f32 v12, v9, v12
	v_lshlrev_b32_e32 v9, 16, v16
	v_add_f32_e32 v67, v67, v49
	v_mul_f32_e32 v9, v13, v9
	v_lshlrev_b32_e32 v13, 16, v17
	v_add_f32_e32 v68, v68, v49
	v_mul_f32_e32 v13, v14, v13
	v_sub_f32_e32 v14, v4, v67
	v_mul_f32_e32 v14, 0x3fb8aa3b, v14
	v_sub_f32_e32 v16, v4, v68
	v_exp_f32_e32 v14, v14
	v_mul_f32_e32 v16, 0x3fb8aa3b, v16
	v_exp_f32_e32 v16, v16
	v_cndmask_b32_e64 v9, 0, v9, s[50:51]
	v_cndmask_b32_e64 v13, 0, v13, s[52:53]
	v_cvt_pk_bf16_f32 v13, v9, v13
	v_lshlrev_b32_e32 v9, 16, v18
	v_mul_f32_e32 v9, v14, v9
	v_lshlrev_b32_e32 v14, 16, v19
	v_mul_f32_e32 v14, v16, v14
	v_add_f32_e32 v63, v63, v49
; #define LAS __attribute__((address_space(3)))
; __device__ __forceinline__ float bf2f(bf16_t b) { return __uint_as_float(((unsigned)b) << 16); }
; __device__ __forceinline__ unsigned cvt_pk_bf16(float lo, float hi) { const f32x2 f = {lo, hi}; const bf16n2 v = __builtin_convertvector(f, bf16n2); return __builtin_bit_cast(unsigned, v); }
; __device__ __forceinline__ void gla_store_vT(const GlaLoads& L, int n, int t4, LAS unsigned char* hl) {
; #pragma unroll
;     for (int q = 0; q < 4; ++q) { const int task = t4 + 256 * q, dv = task & 127, rg = task >> 7; unsigned v[8];
; #pragma unroll
;         for (int j = 0; j < 8; ++j) { const int rb = n * 64 + rg * 8 + j; v[j] = rb < TB ? (unsigned)L.vv[q][j] : 0u; }
;         u32x4 w; w.x = v[0] | (v[1] << 16); w.y = v[2] | (v[3] << 16); w.z = v[4] | (v[5] << 16); w.w = v[6] | (v[7] << 16);
;         *(LAS u32x4*)(hl + GL_VT + dv * 144 + rg * 16) = w; }
; }
; __device__ void gla1_item(const Params& p, int l, int item, LAS unsigned char* lds) {
;     ...
;           const float k0 = rb < TB ? bf2f(L.xk[i]) * __expf(tot - bc[i]) : 0.f, k1 = rb + 1 < TB ? bf2f(L.xk[i + 1]) * __expf(tot - bc[i + 1]) : 0.f;
;           w[i >> 1] = cvt_pk_bf16(k0, k1); }
;       *(LAS u32x4*)(hl + GL_KI + dk * 144 + seg * 32) = (u32x4){w[0], w[1], w[2], w[3]};
;       *(LAS u32x4*)(hl + GL_KI + dk * 144 + seg * 32 + 16) = (u32x4){w[4], w[5], w[6], w[7]}; }
;     gla_store_vT(L, n, t4, hl);
;     if (seg == 0) ((float*)(p.ws + WS_DECAY))[((size_t)bh * GCH + n) * 64 + dk] = __expf(tot);
	v_cndmask_b32_e64 v9, 0, v9, s[54:55]
	v_cndmask_b32_e64 v14, 0, v14, s[56:57]
	v_add_f32_e32 v62, v62, v49
	v_cvt_pk_bf16_f32 v16, v9, v14
	v_sub_f32_e32 v14, v4, v63
	v_mul_f32_e32 v14, 0x3fb8aa3b, v14
	v_sub_f32_e32 v17, v4, v62
	v_exp_f32_e32 v14, v14
	v_mul_f32_e32 v17, 0x3fb8aa3b, v17
	v_exp_f32_e32 v17, v17
	v_lshlrev_b32_e32 v9, 16, v20
	v_mul_f32_e32 v9, v14, v9
	v_lshlrev_b32_e32 v14, 16, v21
	v_mul_f32_e32 v14, v17, v14
	v_add_f32_e32 v57, v57, v49
	v_cndmask_b32_e64 v9, 0, v9, s[58:59]
	v_cndmask_b32_e64 v14, 0, v14, s[60:61]
	v_add_f32_e32 v55, v55, v49
	v_cvt_pk_bf16_f32 v17, v9, v14
	v_sub_f32_e32 v14, v4, v57
	v_mul_f32_e32 v14, 0x3fb8aa3b, v14
	v_sub_f32_e32 v18, v4, v55
	v_exp_f32_e32 v14, v14
	v_mul_f32_e32 v18, 0x3fb8aa3b, v18
	v_exp_f32_e32 v18, v18
	v_lshlrev_b32_e32 v9, 16, v22
	v_mul_f32_e32 v9, v14, v9
	v_lshlrev_b32_e32 v14, 16, v23
	v_mul_f32_e32 v14, v18, v14
	v_add_f32_e32 v51, v51, v49
	v_cndmask_b32_e64 v9, 0, v9, s[62:63]
	v_cndmask_b32_e64 v14, 0, v14, s[66:67]
	v_cvt_pk_bf16_f32 v18, v9, v14
	v_sub_f32_e32 v14, v4, v51
	v_mul_f32_e32 v14, 0x3fb8aa3b, v14
	v_sub_f32_e32 v5, v4, v5
	v_exp_f32_e32 v14, v14
	v_mul_f32_e32 v5, 0x3fb8aa3b, v5
	v_exp_f32_e32 v5, v5
	v_lshlrev_b32_e32 v9, 16, v24
	v_mul_f32_e32 v9, v14, v9
	v_lshlrev_b32_e32 v14, 16, v26
	v_mul_f32_e32 v5, v5, v14
	v_cndmask_b32_e64 v9, 0, v9, s[68:69]
	v_cndmask_b32_e64 v5, 0, v5, s[70:71]
	v_cvt_pk_bf16_f32 v19, v9, v5
	v_mul_u32_u24_e32 v5, 0x90, v7
	v_add3_u32 v5, v15, v5, v6
	v_lshrrev_b32_sdwa v6, v238, v8 dst_sel:DWORD dst_unused:UNUSED_PAD src0_sel:DWORD src1_sel:BYTE_0
	v_lshl_or_b32 v7, v6, 3, v3
	ds_write_b128 v5, v[10:13] offset:9216
	ds_write_b128 v5, v[16:19] offset:9232
	v_cmp_gt_i32_e32 vcc, s0, v7
	v_or_b32_e32 v10, 1, v7
	v_lshlrev_b32_e32 v11, 16, v27
	v_cndmask_b32_e32 v9, 0, v42, vcc
	v_cmp_gt_i32_e32 vcc, s0, v10
	v_or_b32_e32 v12, 3, v7
	v_lshlrev_b32_e32 v13, 16, v28
	v_cndmask_b32_e32 v10, 0, v11, vcc
	v_or_b32_e32 v11, 2, v7
	v_cmp_gt_i32_e32 vcc, s0, v11
	v_or_b32_e32 v14, 5, v7
	v_lshlrev_b32_e32 v16, 16, v29
	v_cndmask_b32_e32 v11, 0, v70, vcc
	v_cmp_gt_i32_e32 vcc, s0, v12
	v_and_b32_e32 v50, 0xffff, v50
	s_movk_i32 s1, 0x90
	v_cndmask_b32_e32 v12, 0, v13, vcc
	v_or_b32_e32 v13, 4, v7
	v_cmp_gt_i32_e32 vcc, s0, v13
	v_lshlrev_b32_e32 v17, 16, v31
	v_mad_u32_u24 v5, v25, s1, v15
	v_cndmask_b32_e32 v13, 0, v71, vcc
	v_cmp_gt_i32_e32 vcc, s0, v14
	v_or_b32_e32 v10, v10, v9
	v_or_b32_e32 v11, v12, v11
	v_cndmask_b32_e32 v14, 0, v16, vcc
	v_or_b32_e32 v16, 6, v7
	v_cmp_gt_i32_e32 vcc, s0, v16
	v_or_b32_e32 v7, 7, v7
	v_or_b32_e32 v12, v14, v13
	v_cndmask_b32_e32 v16, 0, v50, vcc
	v_cmp_gt_i32_e32 vcc, s0, v7
	v_and_b32_e32 v53, 0xffff, v53
	v_and_b32_e32 v56, 0xffff, v56
	v_cndmask_b32_e32 v7, 0, v17, vcc
	v_or_b32_e32 v13, v7, v16
	v_lshl_add_u32 v7, v6, 4, v5
	ds_write_b128 v7, v[10:13] offset:27648
	v_or_b32_e32 v7, 2, v6
	v_lshl_or_b32 v9, v7, 3, v3
	v_cmp_gt_i32_e32 vcc, s0, v9
	v_or_b32_e32 v11, 1, v9
	v_lshlrev_b32_e32 v12, 16, v30
	v_cndmask_b32_e32 v10, 0, v53, vcc
	v_cmp_gt_i32_e32 vcc, s0, v11
	v_or_b32_e32 v13, 3, v9
	v_lshlrev_b32_e32 v14, 16, v32
	v_cndmask_b32_e32 v11, 0, v12, vcc
	v_or_b32_e32 v12, 2, v9
	v_cmp_gt_i32_e32 vcc, s0, v12
	v_and_b32_e32 v58, 0xffff, v58
	v_or_b32_e32 v16, 5, v9
	v_cndmask_b32_e32 v12, 0, v56, vcc
	v_cmp_gt_i32_e32 vcc, s0, v13
	v_lshlrev_b32_e32 v17, 16, v33
	v_and_b32_e32 v61, 0xffff, v61
	v_cndmask_b32_e32 v13, 0, v14, vcc
	v_or_b32_e32 v14, 4, v9
	v_cmp_gt_i32_e32 vcc, s0, v14
	v_lshlrev_b32_e32 v18, 16, v35
	v_or_b32_e32 v10, v11, v10
	v_cndmask_b32_e32 v14, 0, v58, vcc
	v_cmp_gt_i32_e32 vcc, s0, v16
	v_or_b32_e32 v11, v13, v12
	v_lshl_add_u32 v7, v7, 4, v5
	v_cndmask_b32_e32 v16, 0, v17, vcc
	v_or_b32_e32 v17, 6, v9
	v_cmp_gt_i32_e32 vcc, s0, v17
	v_or_b32_e32 v9, 7, v9
	v_or_b32_e32 v12, v16, v14
	v_cndmask_b32_e32 v17, 0, v61, vcc
	v_cmp_gt_i32_e32 vcc, s0, v9
	v_and_b32_e32 v65, 0xffff, v65
	v_and_b32_e32 v66, 0xffff, v66
	v_cndmask_b32_e32 v9, 0, v18, vcc
	v_or_b32_e32 v13, v9, v17
	ds_write_b128 v7, v[10:13] offset:27648
	v_or_b32_e32 v7, 4, v6
	v_lshl_or_b32 v9, v7, 3, v3
	v_cmp_gt_i32_e32 vcc, s0, v9
	v_or_b32_e32 v11, 1, v9
	v_lshlrev_b32_e32 v12, 16, v34
	v_cndmask_b32_e32 v10, 0, v65, vcc
	v_cmp_gt_i32_e32 vcc, s0, v11
	v_or_b32_e32 v13, 3, v9
	v_lshlrev_b32_e32 v14, 16, v36
	v_cndmask_b32_e32 v11, 0, v12, vcc
	v_or_b32_e32 v12, 2, v9
	v_cmp_gt_i32_e32 vcc, s0, v12
	v_and_b32_e32 v69, 0xffff, v69
	v_or_b32_e32 v16, 5, v9
	v_cndmask_b32_e32 v12, 0, v66, vcc
	v_cmp_gt_i32_e32 vcc, s0, v13
	v_lshlrev_b32_e32 v17, 16, v37
	v_and_b32_e32 v72, 0xffff, v72
	v_cndmask_b32_e32 v13, 0, v14, vcc
	v_or_b32_e32 v14, 4, v9
	v_cmp_gt_i32_e32 vcc, s0, v14
	v_lshlrev_b32_e32 v18, 16, v39
	v_or_b32_e32 v6, 6, v6
	v_cndmask_b32_e32 v14, 0, v69, vcc
	v_cmp_gt_i32_e32 vcc, s0, v16
	v_lshl_or_b32 v3, v6, 3, v3
	v_and_b32_e32 v73, 0xffff, v75
	v_cndmask_b32_e32 v16, 0, v17, vcc
	v_or_b32_e32 v17, 6, v9
	v_cmp_gt_i32_e32 vcc, s0, v17
	v_or_b32_e32 v9, 7, v9
	v_or_b32_e32 v10, v11, v10
	v_cndmask_b32_e32 v17, 0, v72, vcc
	v_cmp_gt_i32_e32 vcc, s0, v9
	v_or_b32_e32 v11, v13, v12
	v_or_b32_e32 v12, v16, v14
	v_cndmask_b32_e32 v9, 0, v18, vcc
	v_or_b32_e32 v13, v9, v17
	v_lshl_add_u32 v7, v7, 4, v5
	v_cmp_gt_i32_e32 vcc, s0, v3
	v_or_b32_e32 v9, 1, v3
	ds_write_b128 v7, v[10:13] offset:27648
	v_cndmask_b32_e32 v7, 0, v73, vcc
	v_lshlrev_b32_e32 v10, 16, v38
	v_cmp_gt_i32_e32 vcc, s0, v9
	v_lshlrev_b32_e32 v12, 16, v40
	v_and_b32_e32 v75, 0xffff, v79
	v_cndmask_b32_e32 v9, 0, v10, vcc
	v_or_b32_e32 v10, 2, v3
	v_cmp_gt_i32_e32 vcc, s0, v10
	v_or_b32_e32 v10, 3, v3
	v_lshlrev_b32_e32 v14, 16, v41
	v_cndmask_b32_e32 v11, 0, v74, vcc
	v_cmp_gt_i32_e32 vcc, s0, v10
	v_or_b32_e32 v10, 4, v3
	v_and_b32_e32 v76, 0xffff, v82
	v_cndmask_b32_e32 v12, 0, v12, vcc
	v_cmp_gt_i32_e32 vcc, s0, v10
	v_or_b32_e32 v10, 5, v3
	v_or_b32_e32 v11, v12, v11
	v_cndmask_b32_e32 v13, 0, v75, vcc
	v_cmp_gt_i32_e32 vcc, s0, v10
	v_or_b32_e32 v10, 6, v3
	v_or_b32_e32 v3, 7, v3
	v_cndmask_b32_e32 v14, 0, v14, vcc
	v_cmp_gt_i32_e32 vcc, s0, v10
	v_lshlrev_b32_e32 v10, 16, v43
	v_or_b32_e32 v12, v14, v13
	v_cndmask_b32_e32 v16, 0, v76, vcc
	v_cmp_gt_i32_e32 vcc, s0, v3
	s_mul_i32 s86, s97, 0x42
	s_nop 0
	v_cndmask_b32_e32 v3, 0, v10, vcc
	v_or_b32_e32 v10, v9, v7
	v_or_b32_e32 v13, v3, v16
	v_lshl_add_u32 v3, v6, 4, v5
	ds_write_b128 v3, v[10:13] offset:27648
	v_ashrrev_i32_e32 v3, 31, v2
	s_and_saveexec_b64 s[22:23], s[64:65]
	s_xor_b64 s[22:23], exec, s[22:23]
	v_lshl_add_u64 v[6:7], v[2:3], 0, s[86:87]
	s_andn2_saveexec_b64 s[22:23], s[22:23]
	s_cbranch_execz .LBB0_594
	v_mul_f32_e32 v4, 0x3fb8aa3b, v4
	v_exp_f32_e32 v4, v4
	v_lshl_add_u64 v[6:7], v[2:3], 0, s[86:87]
	v_lshlrev_b64 v[2:3], 8, v[6:7]
	v_lshl_add_u64 v[2:3], s[12:13], 0, v[2:3]
	v_lshl_add_u64 v[2:3], v[2:3], 0, v[0:1]
	global_store_dword v[2:3], v4, off
